# GEMM K-loops: LDS-DMA addresses use scalar base + 32-bit lane offset (SALU sums) instead of a 64-bit VALU add per DMA
# speedup vs baseline: 1.0079x; 1.0046x over previous
; #define PG8_STAGE(bufoff, gbase, voff) do { _Pragma("unroll") for (int _i = 0; _i < 2; ++_i) \
;         __builtin_amdgcn_global_load_lds((const unsigned*)((const char*)(gbase) + (voff)[_i]), (LAS unsigned*)(lds + (bufoff) + ldsw + _i * 8192), 16, 0, 0); } while (0)
; #define PG8_LDA(dst, b, h) do { _Pragma("unroll") for (int m = 0; m < 4; ++m) _Pragma("unroll") for (int k = 0; k < 2; ++k) dst[m][k] = *(const LAS bf16x8*)(lds + PG8_SA(b, h) + aoff + m * 2048 + k * 1024); } while (0)
; #define PG8_LDB(dst, b, h) do { _Pragma("unroll") for (int n = 0; n < 2; ++n) _Pragma("unroll") for (int k = 0; k < 2; ++k) dst[n][k] = *(const LAS bf16x8*)(lds + PG8_SB(b, h) + boff + n * 2048 + k * 1024); } while (0)
; #define PG8_WAIT_V(n) asm volatile("s_waitcnt vmcnt(" #n ")" ::: "memory")
; #define PG8_BAR __builtin_amdgcn_s_barrier()
; template <class EpiT, class Sched>
; __device__ __forceinline__ void gemm_phase(LAS unsigned char* lds, const Gemm g, const Sched& S, const EpiT& E, int wv) {
;     ...
;         for (int t = 0; t < nt; t += 2) {
;             const bool last = (t == nt - 2);
;             const char* a1 = cA + (size_t)(t + 1) * kstep;
;             const char* a2 = last ? nA : cA + (size_t)(t + 2) * kstep; const char* b2 = last ? nB : cB + (size_t)(t + 2) * kstep;
;             const char* a3 = a2 + kstep; const char* b3 = b2 + kstep;
;             PG8_LDB(B0, 0, 0); PG8_LDB(B1, 0, 1); PG8_SCHED; PG8_LDA(At, 0, 0); PG8_STAGE(PG8_SA(1, 1), a1 + hstepA, voffA);
;             PG8_WAIT_V(8); PG8_WAIT_L(0); PG8_BAR; PG8_MMA(0, 0, At, B0); PG8_MMA(0, 1, At, B1); PG8_BAR; PG8_SCHED;
;             PG8_LDA(At, 0, 1); PG8_STAGE(PG8_SB(0, 0), b2, voffB); PG8_STAGE(PG8_SB(0, 1), b2 + hstepB, voffB); PG8_STAGE(PG8_SA(0, 0), a2, voffA);
;             PG8_WAIT_V(8); PG8_WAIT_L(0); PG8_BAR; PG8_MMA(1, 0, At, B0); PG8_MMA(1, 1, At, B1); PG8_BAR; PG8_SCHED;
;             PG8_LDB(B0, 1, 0); PG8_LDB(B1, 1, 1); PG8_SCHED; PG8_LDA(At, 1, 0); PG8_STAGE(PG8_SA(0, 1), a2 + hstepA, voffA);
;             PG8_WAIT_V(8); PG8_WAIT_L(0); PG8_BAR; PG8_MMA(0, 0, At, B0); PG8_MMA(0, 1, At, B1); PG8_BAR; PG8_SCHED;
;             PG8_LDA(At, 1, 1); PG8_STAGE(PG8_SB(1, 0), b3, voffB); PG8_STAGE(PG8_SB(1, 1), b3 + hstepB, voffB); PG8_STAGE(PG8_SA(1, 0), a3, voffA);
;             PG8_WAIT_V(8); PG8_WAIT_L(0); PG8_BAR; PG8_MMA(1, 0, At, B0); PG8_MMA(1, 1, At, B1); PG8_BAR; PG8_SCHED;
;         }
.LBB0_246:
	s_add_u32 s28, s26, 0xfffc0080
	s_addc_u32 s29, s27, -1
	s_add_i32 s50, 0, 0x10000
	s_cmp_eq_u32 s49, 12
	s_cselect_b32 s31, s19, s29
	s_cselect_b32 s30, s25, s28
	s_cselect_b32 s29, s17, s48
	s_cselect_b32 s28, s46, s47
	s_add_i32 s52, 0, 0x14000
	v_add_u32_e32 v150, s50, v164
	v_add_u32_e32 v162, s52, v164
	ds_read_b128 v[128:131], v150
	ds_read_b128 v[132:135], v150 offset:1024
	ds_read_b128 v[146:149], v150 offset:2048
	ds_read_b128 v[150:153], v150 offset:3072
	ds_read_b128 v[154:157], v162
	ds_read_b128 v[158:161], v162 offset:1024
	ds_read_b128 v[166:169], v162 offset:2048
	ds_read_b128 v[170:173], v162 offset:3072
	s_add_i32 m0, s36, 0xc000
	ds_read_b128 v[174:177], v165
	ds_read_b128 v[178:181], v165 offset:1024
	ds_read_b128 v[182:185], v165 offset:2048
	ds_read_b128 v[186:189], v165 offset:3072
	ds_read_b128 v[204:207], v165 offset:4096
	ds_read_b128 v[208:211], v165 offset:5120
	ds_read_b128 v[212:215], v165 offset:6144
	ds_read_b128 v[216:219], v165 offset:7168
	global_load_lds_dwordx4 v142, s[26:27]
	s_add_i32 m0, s36, 0xe000
	s_nop 0
	global_load_lds_dwordx4 v144, s[26:27]
	s_waitcnt vmcnt(8)
	s_waitcnt lgkmcnt(0)
	s_barrier
	s_setprio 1
	s_waitcnt lgkmcnt(0)
	v_mfma_f32_16x16x32_bf16 v[124:127], v[128:131], v[174:177], v[124:127]
	v_mfma_f32_16x16x32_bf16 v[120:123], v[146:149], v[174:177], v[120:123]
	v_mfma_f32_16x16x32_bf16 v[116:119], v[128:131], v[182:185], v[116:119]
	v_mfma_f32_16x16x32_bf16 v[112:115], v[146:149], v[182:185], v[112:115]
	v_mfma_f32_16x16x32_bf16 v[108:111], v[128:131], v[204:207], v[108:111]
	v_mfma_f32_16x16x32_bf16 v[104:107], v[146:149], v[204:207], v[104:107]
	v_mfma_f32_16x16x32_bf16 v[100:103], v[128:131], v[212:215], v[100:103]
	v_mfma_f32_16x16x32_bf16 v[96:99], v[146:149], v[212:215], v[96:99]
	v_mfma_f32_16x16x32_bf16 v[124:127], v[132:135], v[178:181], v[124:127]
	v_mfma_f32_16x16x32_bf16 v[120:123], v[150:153], v[178:181], v[120:123]
	v_mfma_f32_16x16x32_bf16 v[116:119], v[132:135], v[186:189], v[116:119]
	v_mfma_f32_16x16x32_bf16 v[112:115], v[150:153], v[186:189], v[112:115]
	v_mfma_f32_16x16x32_bf16 v[108:111], v[132:135], v[208:211], v[108:111]
	v_mfma_f32_16x16x32_bf16 v[104:107], v[150:153], v[208:211], v[104:107]
	v_mfma_f32_16x16x32_bf16 v[100:103], v[132:135], v[216:219], v[100:103]
	v_mfma_f32_16x16x32_bf16 v[96:99], v[150:153], v[216:219], v[96:99]
	s_setprio 0
	s_setprio 1
	v_mfma_f32_16x16x32_bf16 v[64:67], v[154:157], v[174:177], v[64:67]
	v_mfma_f32_16x16x32_bf16 v[56:59], v[166:169], v[174:177], v[56:59]
	v_mfma_f32_16x16x32_bf16 v[52:55], v[154:157], v[182:185], v[52:55]
	v_mfma_f32_16x16x32_bf16 v[48:51], v[166:169], v[182:185], v[48:51]
	v_mfma_f32_16x16x32_bf16 v[44:47], v[154:157], v[204:207], v[44:47]
	v_mfma_f32_16x16x32_bf16 v[40:43], v[166:169], v[204:207], v[40:43]
	v_mfma_f32_16x16x32_bf16 v[36:39], v[154:157], v[212:215], v[36:39]
	v_mfma_f32_16x16x32_bf16 v[32:35], v[166:169], v[212:215], v[32:35]
	v_mfma_f32_16x16x32_bf16 v[64:67], v[158:161], v[178:181], v[64:67]
	v_mfma_f32_16x16x32_bf16 v[56:59], v[170:173], v[178:181], v[56:59]
	v_mfma_f32_16x16x32_bf16 v[52:55], v[158:161], v[186:189], v[52:55]
	v_mfma_f32_16x16x32_bf16 v[48:51], v[170:173], v[186:189], v[48:51]
	v_mfma_f32_16x16x32_bf16 v[44:47], v[158:161], v[208:211], v[44:47]
	v_mfma_f32_16x16x32_bf16 v[40:43], v[170:173], v[208:211], v[40:43]
	v_mfma_f32_16x16x32_bf16 v[36:39], v[158:161], v[216:219], v[36:39]
	v_mfma_f32_16x16x32_bf16 v[32:35], v[170:173], v[216:219], v[32:35]
	s_setprio 0
	s_barrier
	s_add_i32 s50, s50, s35
	s_add_u32 s54, s28, s92
	s_addc_u32 s55, s29, s93
	s_mov_b32 m0, s50
	ds_read_b128 v[174:177], v165 offset:16384
	ds_read_b128 v[178:181], v165 offset:17408
	ds_read_b128 v[182:185], v165 offset:18432
	ds_read_b128 v[186:189], v165 offset:19456
	ds_read_b128 v[204:207], v165 offset:20480
	ds_read_b128 v[208:211], v165 offset:21504
	ds_read_b128 v[212:215], v165 offset:22528
	ds_read_b128 v[216:219], v165 offset:23552
	global_load_lds_dwordx4 v192, s[28:29]
	s_add_i32 m0, s50, 0x2000
	s_add_u32 s50, s28, 0x40000
	s_addc_u32 s51, s29, 0
	s_add_i32 s52, s52, s35
	global_load_lds_dwordx4 v140, s[28:29]
	s_mov_b32 m0, s52
	s_nop 0
	global_load_lds_dwordx4 v192, s[50:51]
	s_add_i32 m0, s52, 0x2000
	s_nop 0
	global_load_lds_dwordx4 v140, s[50:51]
	s_add_u32 s56, s30, s92
	s_addc_u32 s57, s31, s93
	s_mov_b32 m0, s36
	s_nop 0
	global_load_lds_dwordx4 v136, s[30:31]
	s_mov_b32 m0, s37
	s_nop 0
	global_load_lds_dwordx4 v138, s[30:31]
	s_waitcnt vmcnt(8)
	s_waitcnt lgkmcnt(0)
	s_barrier
; #define PG8_STAGE(bufoff, gbase, voff) do { _Pragma("unroll") for (int _i = 0; _i < 2; ++_i) \
;         __builtin_amdgcn_global_load_lds((const unsigned*)((const char*)(gbase) + (voff)[_i]), (LAS unsigned*)(lds + (bufoff) + ldsw + _i * 8192), 16, 0, 0); } while (0)
; #define PG8_LDA(dst, b, h) do { _Pragma("unroll") for (int m = 0; m < 4; ++m) _Pragma("unroll") for (int k = 0; k < 2; ++k) dst[m][k] = *(const LAS bf16x8*)(lds + PG8_SA(b, h) + aoff + m * 2048 + k * 1024); } while (0)
; #define PG8_LDB(dst, b, h) do { _Pragma("unroll") for (int n = 0; n < 2; ++n) _Pragma("unroll") for (int k = 0; k < 2; ++k) dst[n][k] = *(const LAS bf16x8*)(lds + PG8_SB(b, h) + boff + n * 2048 + k * 1024); } while (0)
; #define PG8_MMA(ai, bj, At, Bt) do { __builtin_amdgcn_s_setprio(1); _Pragma("unroll") for (int m = 0; m < 4; ++m) _Pragma("unroll") for (int n = 0; n < 2; ++n) _Pragma("unroll") for (int k = 0; k < 2; ++k) \
;         acc[ai][bj][m][n] = __builtin_amdgcn_mfma_f32_16x16x32_bf16(Bt[n][k], At[m][k], acc[ai][bj][m][n], 0, 0, 0); __builtin_amdgcn_s_setprio(0); } while (0)
; #define PG8_WAIT_V(n) asm volatile("s_waitcnt vmcnt(" #n ")" ::: "memory")
; #define PG8_WAIT_L(n) asm volatile("s_waitcnt lgkmcnt(" #n ")" ::: "memory")
; #define PG8_BAR __builtin_amdgcn_s_barrier()
; #define PG8_SCHED __builtin_amdgcn_sched_barrier(0)
; template <class EpiT, class Sched>
; __device__ __forceinline__ void gemm_phase(LAS unsigned char* lds, const Gemm g, const Sched& S, const EpiT& E, int wv) {
;     ...
;             PG8_WAIT_V(8); PG8_WAIT_L(0); PG8_BAR; PG8_MMA(1, 0, At, B0); PG8_MMA(1, 1, At, B1); PG8_BAR; PG8_SCHED;
;             PG8_LDB(B0, 1, 0); PG8_LDB(B1, 1, 1); PG8_SCHED; PG8_LDA(At, 1, 0); PG8_STAGE(PG8_SA(0, 1), a2 + hstepA, voffA);
;             PG8_WAIT_V(8); PG8_WAIT_L(0); PG8_BAR; PG8_MMA(0, 0, At, B0); PG8_MMA(0, 1, At, B1); PG8_BAR; PG8_SCHED;
;             PG8_LDA(At, 1, 1); PG8_STAGE(PG8_SB(1, 0), b3, voffB); PG8_STAGE(PG8_SB(1, 1), b3 + hstepB, voffB); PG8_STAGE(PG8_SA(1, 0), a3, voffA);
	s_setprio 1
	s_waitcnt lgkmcnt(0)
	v_mfma_f32_16x16x32_bf16 v[92:95], v[128:131], v[174:177], v[92:95]
	v_mfma_f32_16x16x32_bf16 v[88:91], v[146:149], v[174:177], v[88:91]
	v_mfma_f32_16x16x32_bf16 v[84:87], v[128:131], v[182:185], v[84:87]
	v_mfma_f32_16x16x32_bf16 v[80:83], v[146:149], v[182:185], v[80:83]
	v_mfma_f32_16x16x32_bf16 v[76:79], v[128:131], v[204:207], v[76:79]
	v_mfma_f32_16x16x32_bf16 v[72:75], v[146:149], v[204:207], v[72:75]
	v_mfma_f32_16x16x32_bf16 v[68:71], v[128:131], v[212:215], v[68:71]
	v_mfma_f32_16x16x32_bf16 v[60:63], v[146:149], v[212:215], v[60:63]
	v_mfma_f32_16x16x32_bf16 v[92:95], v[132:135], v[178:181], v[92:95]
	v_mfma_f32_16x16x32_bf16 v[88:91], v[150:153], v[178:181], v[88:91]
	v_mfma_f32_16x16x32_bf16 v[84:87], v[132:135], v[186:189], v[84:87]
	v_mfma_f32_16x16x32_bf16 v[80:83], v[150:153], v[186:189], v[80:83]
	v_mfma_f32_16x16x32_bf16 v[76:79], v[132:135], v[208:211], v[76:79]
	v_mfma_f32_16x16x32_bf16 v[72:75], v[150:153], v[208:211], v[72:75]
	v_mfma_f32_16x16x32_bf16 v[68:71], v[132:135], v[216:219], v[68:71]
	v_mfma_f32_16x16x32_bf16 v[60:63], v[150:153], v[216:219], v[60:63]
	s_setprio 0
	s_setprio 1
	v_mfma_f32_16x16x32_bf16 v[28:31], v[154:157], v[174:177], v[28:31]
	v_mfma_f32_16x16x32_bf16 v[24:27], v[166:169], v[174:177], v[24:27]
	v_mfma_f32_16x16x32_bf16 v[20:23], v[154:157], v[182:185], v[20:23]
	v_mfma_f32_16x16x32_bf16 v[16:19], v[166:169], v[182:185], v[16:19]
	v_mfma_f32_16x16x32_bf16 v[12:15], v[154:157], v[204:207], v[12:15]
	v_mfma_f32_16x16x32_bf16 v[8:11], v[166:169], v[204:207], v[8:11]
	v_mfma_f32_16x16x32_bf16 v[4:7], v[154:157], v[212:215], v[4:7]
	v_mfma_f32_16x16x32_bf16 v[0:3], v[166:169], v[212:215], v[0:3]
	v_mfma_f32_16x16x32_bf16 v[28:31], v[158:161], v[178:181], v[28:31]
	v_mfma_f32_16x16x32_bf16 v[24:27], v[170:173], v[178:181], v[24:27]
	v_mfma_f32_16x16x32_bf16 v[20:23], v[158:161], v[186:189], v[20:23]
	v_mfma_f32_16x16x32_bf16 v[16:19], v[170:173], v[186:189], v[16:19]
	v_mfma_f32_16x16x32_bf16 v[12:15], v[158:161], v[208:211], v[12:15]
	v_mfma_f32_16x16x32_bf16 v[8:11], v[170:173], v[208:211], v[8:11]
	v_mfma_f32_16x16x32_bf16 v[4:7], v[158:161], v[216:219], v[4:7]
	v_mfma_f32_16x16x32_bf16 v[0:3], v[170:173], v[216:219], v[0:3]
	s_setprio 0
	s_barrier
	s_add_i32 s50, 0, 0x18000
	s_add_i32 s51, 0, 0x1c000
	v_add_u32_e32 v150, s50, v164
	v_add_u32_e32 v170, s51, v164
	ds_read_b128 v[128:131], v150
	ds_read_b128 v[132:135], v150 offset:1024
	ds_read_b128 v[146:149], v150 offset:2048
	ds_read_b128 v[150:153], v150 offset:3072
	ds_read_b128 v[154:157], v170
	ds_read_b128 v[158:161], v170 offset:1024
	ds_read_b128 v[166:169], v170 offset:2048
	ds_read_b128 v[170:173], v170 offset:3072
	s_add_u32 s30, s30, 0x40000
	s_addc_u32 s31, s31, 0
	s_mov_b32 m0, s38
	ds_read_b128 v[174:177], v165 offset:32768
	ds_read_b128 v[178:181], v165 offset:33792
	ds_read_b128 v[182:185], v165 offset:34816
	ds_read_b128 v[186:189], v165 offset:35840
	ds_read_b128 v[204:207], v165 offset:36864
	ds_read_b128 v[208:211], v165 offset:37888
	ds_read_b128 v[212:215], v165 offset:38912
	ds_read_b128 v[216:219], v165 offset:39936
	global_load_lds_dwordx4 v136, s[30:31]
	s_mov_b32 m0, s39
	s_nop 0
	global_load_lds_dwordx4 v138, s[30:31]
	s_waitcnt vmcnt(8)
	s_waitcnt lgkmcnt(0)
	s_barrier
	s_setprio 1
	s_waitcnt lgkmcnt(0)
	v_mfma_f32_16x16x32_bf16 v[124:127], v[128:131], v[174:177], v[124:127]
	v_mfma_f32_16x16x32_bf16 v[120:123], v[146:149], v[174:177], v[120:123]
	v_mfma_f32_16x16x32_bf16 v[116:119], v[128:131], v[182:185], v[116:119]
	v_mfma_f32_16x16x32_bf16 v[112:115], v[146:149], v[182:185], v[112:115]
	v_mfma_f32_16x16x32_bf16 v[108:111], v[128:131], v[204:207], v[108:111]
	v_mfma_f32_16x16x32_bf16 v[104:107], v[146:149], v[204:207], v[104:107]
	v_mfma_f32_16x16x32_bf16 v[100:103], v[128:131], v[212:215], v[100:103]
	v_mfma_f32_16x16x32_bf16 v[96:99], v[146:149], v[212:215], v[96:99]
	v_mfma_f32_16x16x32_bf16 v[124:127], v[132:135], v[178:181], v[124:127]
	v_mfma_f32_16x16x32_bf16 v[120:123], v[150:153], v[178:181], v[120:123]
	v_mfma_f32_16x16x32_bf16 v[116:119], v[132:135], v[186:189], v[116:119]
	v_mfma_f32_16x16x32_bf16 v[112:115], v[150:153], v[186:189], v[112:115]
	v_mfma_f32_16x16x32_bf16 v[108:111], v[132:135], v[208:211], v[108:111]
	v_mfma_f32_16x16x32_bf16 v[104:107], v[150:153], v[208:211], v[104:107]
	v_mfma_f32_16x16x32_bf16 v[100:103], v[132:135], v[216:219], v[100:103]
	v_mfma_f32_16x16x32_bf16 v[96:99], v[150:153], v[216:219], v[96:99]
	s_setprio 0
	s_setprio 1
	v_mfma_f32_16x16x32_bf16 v[64:67], v[154:157], v[174:177], v[64:67]
	v_mfma_f32_16x16x32_bf16 v[56:59], v[166:169], v[174:177], v[56:59]
	v_mfma_f32_16x16x32_bf16 v[52:55], v[154:157], v[182:185], v[52:55]
	v_mfma_f32_16x16x32_bf16 v[48:51], v[166:169], v[182:185], v[48:51]
	v_mfma_f32_16x16x32_bf16 v[44:47], v[154:157], v[204:207], v[44:47]
	v_mfma_f32_16x16x32_bf16 v[40:43], v[166:169], v[204:207], v[40:43]
	v_mfma_f32_16x16x32_bf16 v[36:39], v[154:157], v[212:215], v[36:39]
	v_mfma_f32_16x16x32_bf16 v[32:35], v[166:169], v[212:215], v[32:35]
	v_mfma_f32_16x16x32_bf16 v[64:67], v[158:161], v[178:181], v[64:67]
	v_mfma_f32_16x16x32_bf16 v[56:59], v[170:173], v[178:181], v[56:59]
	v_mfma_f32_16x16x32_bf16 v[52:55], v[158:161], v[186:189], v[52:55]
	v_mfma_f32_16x16x32_bf16 v[48:51], v[170:173], v[186:189], v[48:51]
	v_mfma_f32_16x16x32_bf16 v[44:47], v[158:161], v[208:211], v[44:47]
	v_mfma_f32_16x16x32_bf16 v[40:43], v[170:173], v[208:211], v[40:43]
	v_mfma_f32_16x16x32_bf16 v[36:39], v[158:161], v[216:219], v[36:39]
	v_mfma_f32_16x16x32_bf16 v[32:35], v[170:173], v[216:219], v[32:35]
	s_setprio 0
	s_barrier
; #define PG8_STAGE(bufoff, gbase, voff) do { _Pragma("unroll") for (int _i = 0; _i < 2; ++_i) \
;         __builtin_amdgcn_global_load_lds((const unsigned*)((const char*)(gbase) + (voff)[_i]), (LAS unsigned*)(lds + (bufoff) + ldsw + _i * 8192), 16, 0, 0); } while (0)
; #define PG8_LDA(dst, b, h) do { _Pragma("unroll") for (int m = 0; m < 4; ++m) _Pragma("unroll") for (int k = 0; k < 2; ++k) dst[m][k] = *(const LAS bf16x8*)(lds + PG8_SA(b, h) + aoff + m * 2048 + k * 1024); } while (0)
; #define PG8_MMA(ai, bj, At, Bt) do { __builtin_amdgcn_s_setprio(1); _Pragma("unroll") for (int m = 0; m < 4; ++m) _Pragma("unroll") for (int n = 0; n < 2; ++n) _Pragma("unroll") for (int k = 0; k < 2; ++k) \
;         acc[ai][bj][m][n] = __builtin_amdgcn_mfma_f32_16x16x32_bf16(Bt[n][k], At[m][k], acc[ai][bj][m][n], 0, 0, 0); __builtin_amdgcn_s_setprio(0); } while (0)
; #define PG8_WAIT_V(n) asm volatile("s_waitcnt vmcnt(" #n ")" ::: "memory")
; #define PG8_WAIT_L(n) asm volatile("s_waitcnt lgkmcnt(" #n ")" ::: "memory")
; #define PG8_BAR __builtin_amdgcn_s_barrier()
; #define PG8_SCHED __builtin_amdgcn_sched_barrier(0)
; template <class EpiT, class Sched>
; __device__ __forceinline__ void gemm_phase(LAS unsigned char* lds, const Gemm g, const Sched& S, const EpiT& E, int wv) {
;     ...
;             PG8_LDA(At, 1, 1); PG8_STAGE(PG8_SB(1, 0), b3, voffB); PG8_STAGE(PG8_SB(1, 1), b3 + hstepB, voffB); PG8_STAGE(PG8_SA(1, 0), a3, voffA);
;             PG8_WAIT_V(8); PG8_WAIT_L(0); PG8_BAR; PG8_MMA(1, 0, At, B0); PG8_MMA(1, 1, At, B1); PG8_BAR; PG8_SCHED;
;         }
	s_add_i32 s30, s50, s35
	s_mov_b32 m0, s30
	ds_read_b128 v[174:177], v165 offset:49152
	ds_read_b128 v[178:181], v165 offset:50176
	ds_read_b128 v[182:185], v165 offset:51200
	ds_read_b128 v[186:189], v165 offset:52224
	ds_read_b128 v[204:207], v165 offset:53248
	ds_read_b128 v[208:211], v165 offset:54272
	ds_read_b128 v[212:215], v165 offset:55296
	ds_read_b128 v[216:219], v165 offset:56320
	global_load_lds_dwordx4 v192, s[54:55]
	s_add_i32 m0, s30, 0x2000
	s_add_u32 s28, s28, 0x40080
	s_addc_u32 s29, s29, 0
	s_add_i32 s30, s51, s35
	global_load_lds_dwordx4 v140, s[54:55]
	s_mov_b32 m0, s30
	s_nop 0
	global_load_lds_dwordx4 v192, s[28:29]
	s_add_i32 m0, s30, 0x2000
	s_nop 0
	global_load_lds_dwordx4 v140, s[28:29]
	s_mov_b32 m0, s40
	s_nop 0
	global_load_lds_dwordx4 v136, s[56:57]
	s_mov_b32 m0, s41
	s_nop 0
	global_load_lds_dwordx4 v138, s[56:57]
	s_waitcnt vmcnt(8)
	s_waitcnt lgkmcnt(0)
	s_barrier
	s_setprio 1
	s_waitcnt lgkmcnt(0)
	v_mfma_f32_16x16x32_bf16 v[92:95], v[128:131], v[174:177], v[92:95]
	v_mfma_f32_16x16x32_bf16 v[88:91], v[146:149], v[174:177], v[88:91]
	v_mfma_f32_16x16x32_bf16 v[84:87], v[128:131], v[182:185], v[84:87]
	v_mfma_f32_16x16x32_bf16 v[80:83], v[146:149], v[182:185], v[80:83]
	v_mfma_f32_16x16x32_bf16 v[76:79], v[128:131], v[204:207], v[76:79]
	v_mfma_f32_16x16x32_bf16 v[72:75], v[146:149], v[204:207], v[72:75]
	v_mfma_f32_16x16x32_bf16 v[68:71], v[128:131], v[212:215], v[68:71]
	v_mfma_f32_16x16x32_bf16 v[60:63], v[146:149], v[212:215], v[60:63]
	v_mfma_f32_16x16x32_bf16 v[92:95], v[132:135], v[178:181], v[92:95]
	v_mfma_f32_16x16x32_bf16 v[88:91], v[150:153], v[178:181], v[88:91]
	v_mfma_f32_16x16x32_bf16 v[84:87], v[132:135], v[186:189], v[84:87]
	v_mfma_f32_16x16x32_bf16 v[80:83], v[150:153], v[186:189], v[80:83]
	v_mfma_f32_16x16x32_bf16 v[76:79], v[132:135], v[208:211], v[76:79]
	v_mfma_f32_16x16x32_bf16 v[72:75], v[150:153], v[208:211], v[72:75]
	v_mfma_f32_16x16x32_bf16 v[68:71], v[132:135], v[216:219], v[68:71]
	v_mfma_f32_16x16x32_bf16 v[60:63], v[150:153], v[216:219], v[60:63]
	s_setprio 0
	s_setprio 1
	v_mfma_f32_16x16x32_bf16 v[28:31], v[154:157], v[174:177], v[28:31]
	v_mfma_f32_16x16x32_bf16 v[24:27], v[166:169], v[174:177], v[24:27]
	v_mfma_f32_16x16x32_bf16 v[20:23], v[154:157], v[182:185], v[20:23]
	v_mfma_f32_16x16x32_bf16 v[16:19], v[166:169], v[182:185], v[16:19]
	v_mfma_f32_16x16x32_bf16 v[12:15], v[154:157], v[204:207], v[12:15]
	v_mfma_f32_16x16x32_bf16 v[8:11], v[166:169], v[204:207], v[8:11]
	v_mfma_f32_16x16x32_bf16 v[4:7], v[154:157], v[212:215], v[4:7]
	v_mfma_f32_16x16x32_bf16 v[0:3], v[166:169], v[212:215], v[0:3]
	v_mfma_f32_16x16x32_bf16 v[28:31], v[158:161], v[178:181], v[28:31]
	v_mfma_f32_16x16x32_bf16 v[24:27], v[170:173], v[178:181], v[24:27]
	v_mfma_f32_16x16x32_bf16 v[20:23], v[158:161], v[186:189], v[20:23]
	v_mfma_f32_16x16x32_bf16 v[16:19], v[170:173], v[186:189], v[16:19]
	v_mfma_f32_16x16x32_bf16 v[12:15], v[158:161], v[208:211], v[12:15]
	v_mfma_f32_16x16x32_bf16 v[8:11], v[170:173], v[208:211], v[8:11]
	v_mfma_f32_16x16x32_bf16 v[4:7], v[158:161], v[216:219], v[4:7]
	v_mfma_f32_16x16x32_bf16 v[0:3], v[170:173], v[216:219], v[0:3]
	s_setprio 0
	s_barrier
	s_add_i32 s49, s49, 2
	s_add_u32 s26, s26, 0x100
	s_addc_u32 s27, s27, 0
	s_add_u32 s47, s47, 0x100
	s_addc_u32 s48, s48, 0
	s_cmp_gt_u32 s49, 13
	s_cbranch_scc0 .LBB0_246
	s_and_b64 vcc, exec, s[12:13]
	s_cbranch_vccz .LBB0_249
	s_barrier

; #define PG8_STAGE(bufoff, gbase, voff) do { _Pragma("unroll") for (int _i = 0; _i < 2; ++_i) \
;         __builtin_amdgcn_global_load_lds((const unsigned*)((const char*)(gbase) + (voff)[_i]), (LAS unsigned*)(lds + (bufoff) + ldsw + _i * 8192), 16, 0, 0); } while (0)
; #define PG8_LDA(dst, b, h) do { _Pragma("unroll") for (int m = 0; m < 4; ++m) _Pragma("unroll") for (int k = 0; k < 2; ++k) dst[m][k] = *(const LAS bf16x8*)(lds + PG8_SA(b, h) + aoff + m * 2048 + k * 1024); } while (0)
; #define PG8_LDB(dst, b, h) do { _Pragma("unroll") for (int n = 0; n < 2; ++n) _Pragma("unroll") for (int k = 0; k < 2; ++k) dst[n][k] = *(const LAS bf16x8*)(lds + PG8_SB(b, h) + boff + n * 2048 + k * 1024); } while (0)
; #define PG8_MMA(ai, bj, At, Bt) do { __builtin_amdgcn_s_setprio(1); _Pragma("unroll") for (int m = 0; m < 4; ++m) _Pragma("unroll") for (int n = 0; n < 2; ++n) _Pragma("unroll") for (int k = 0; k < 2; ++k) \
;         acc[ai][bj][m][n] = __builtin_amdgcn_mfma_f32_16x16x32_bf16(Bt[n][k], At[m][k], acc[ai][bj][m][n], 0, 0, 0); __builtin_amdgcn_s_setprio(0); } while (0)
; #define PG8_WAIT_V(n) asm volatile("s_waitcnt vmcnt(" #n ")" ::: "memory")
; #define PG8_WAIT_L(n) asm volatile("s_waitcnt lgkmcnt(" #n ")" ::: "memory")
; #define PG8_BAR __builtin_amdgcn_s_barrier()
; #define PG8_SCHED __builtin_amdgcn_sched_barrier(0)
; template <class EpiT, class Sched>
; __device__ __forceinline__ void gemm_phase(LAS unsigned char* lds, const Gemm g, const Sched& S, const EpiT& E, int wv) {
;     ...
;         for (int t = 0; t < nt; t += 2) {
;             const bool last = (t == nt - 2);
;             const char* a1 = cA + (size_t)(t + 1) * kstep;
;             const char* a2 = last ? nA : cA + (size_t)(t + 2) * kstep; const char* b2 = last ? nB : cB + (size_t)(t + 2) * kstep;
;             const char* a3 = a2 + kstep; const char* b3 = b2 + kstep;
;             PG8_LDB(B0, 0, 0); PG8_LDB(B1, 0, 1); PG8_SCHED; PG8_LDA(At, 0, 0); PG8_STAGE(PG8_SA(1, 1), a1 + hstepA, voffA);
;             PG8_WAIT_V(8); PG8_WAIT_L(0); PG8_BAR; PG8_MMA(0, 0, At, B0); PG8_MMA(0, 1, At, B1); PG8_BAR; PG8_SCHED;
;             PG8_LDA(At, 0, 1); PG8_STAGE(PG8_SB(0, 0), b2, voffB); PG8_STAGE(PG8_SB(0, 1), b2 + hstepB, voffB); PG8_STAGE(PG8_SA(0, 0), a2, voffA);
;             PG8_WAIT_V(8); PG8_WAIT_L(0); PG8_BAR; PG8_MMA(1, 0, At, B0); PG8_MMA(1, 1, At, B1); PG8_BAR; PG8_SCHED;
.LBB0_1042:
	s_add_u32 s24, s22, 0xfff80080
	s_addc_u32 s25, s23, -1
	s_add_i32 s56, 0, 0x10000
	s_cmp_eq_u32 s55, 4
	s_cselect_b32 s27, s1, s25
	s_cselect_b32 s26, s15, s24
	s_cselect_b32 s25, s13, s54
	s_cselect_b32 s24, s33, s53
	s_add_i32 s58, 0, 0x14000
	v_add_u32_e32 v140, s56, v212
	v_add_u32_e32 v166, s58, v212
	ds_read_b128 v[128:131], v140
	ds_read_b128 v[132:135], v140 offset:1024
	ds_read_b128 v[136:139], v140 offset:2048
	ds_read_b128 v[140:143], v140 offset:3072
	ds_read_b128 v[144:147], v166
	ds_read_b128 v[148:151], v166 offset:1024
	ds_read_b128 v[152:155], v166 offset:2048
	ds_read_b128 v[166:169], v166 offset:3072
	s_add_i32 m0, s21, 0xc000
	ds_read_b128 v[170:173], v213
	ds_read_b128 v[174:177], v213 offset:1024
	ds_read_b128 v[178:181], v213 offset:2048
	ds_read_b128 v[182:185], v213 offset:3072
	ds_read_b128 v[186:189], v213 offset:4096
	ds_read_b128 v[204:207], v213 offset:5120
	ds_read_b128 v[208:211], v213 offset:6144
	ds_read_b128 v[214:217], v213 offset:7168
	global_load_lds_dwordx4 v162, s[22:23]
	s_add_i32 m0, s21, 0xe000
	s_nop 0
	global_load_lds_dwordx4 v164, s[22:23]
	s_waitcnt vmcnt(8)
	s_waitcnt lgkmcnt(0)
	s_barrier
	s_setprio 1
	s_waitcnt lgkmcnt(0)
	v_mfma_f32_16x16x32_bf16 v[124:127], v[128:131], v[170:173], v[124:127]
	v_mfma_f32_16x16x32_bf16 v[120:123], v[136:139], v[170:173], v[120:123]
	v_mfma_f32_16x16x32_bf16 v[116:119], v[128:131], v[178:181], v[116:119]
	v_mfma_f32_16x16x32_bf16 v[112:115], v[136:139], v[178:181], v[112:115]
	v_mfma_f32_16x16x32_bf16 v[108:111], v[128:131], v[186:189], v[108:111]
	v_mfma_f32_16x16x32_bf16 v[104:107], v[136:139], v[186:189], v[104:107]
	v_mfma_f32_16x16x32_bf16 v[100:103], v[128:131], v[208:211], v[100:103]
	v_mfma_f32_16x16x32_bf16 v[96:99], v[136:139], v[208:211], v[96:99]
	v_mfma_f32_16x16x32_bf16 v[124:127], v[132:135], v[174:177], v[124:127]
	v_mfma_f32_16x16x32_bf16 v[120:123], v[140:143], v[174:177], v[120:123]
	v_mfma_f32_16x16x32_bf16 v[116:119], v[132:135], v[182:185], v[116:119]
	v_mfma_f32_16x16x32_bf16 v[112:115], v[140:143], v[182:185], v[112:115]
	v_mfma_f32_16x16x32_bf16 v[108:111], v[132:135], v[204:207], v[108:111]
	v_mfma_f32_16x16x32_bf16 v[104:107], v[140:143], v[204:207], v[104:107]
	v_mfma_f32_16x16x32_bf16 v[100:103], v[132:135], v[214:217], v[100:103]
	v_mfma_f32_16x16x32_bf16 v[96:99], v[140:143], v[214:217], v[96:99]
	s_setprio 0
	s_setprio 1
	v_mfma_f32_16x16x32_bf16 v[60:63], v[144:147], v[170:173], v[60:63]
	v_mfma_f32_16x16x32_bf16 v[56:59], v[152:155], v[170:173], v[56:59]
	v_mfma_f32_16x16x32_bf16 v[52:55], v[144:147], v[178:181], v[52:55]
	v_mfma_f32_16x16x32_bf16 v[48:51], v[152:155], v[178:181], v[48:51]
	v_mfma_f32_16x16x32_bf16 v[44:47], v[144:147], v[186:189], v[44:47]
	v_mfma_f32_16x16x32_bf16 v[40:43], v[152:155], v[186:189], v[40:43]
	v_mfma_f32_16x16x32_bf16 v[36:39], v[144:147], v[208:211], v[36:39]
	v_mfma_f32_16x16x32_bf16 v[32:35], v[152:155], v[208:211], v[32:35]
	v_mfma_f32_16x16x32_bf16 v[60:63], v[148:151], v[174:177], v[60:63]
	v_mfma_f32_16x16x32_bf16 v[56:59], v[166:169], v[174:177], v[56:59]
	v_mfma_f32_16x16x32_bf16 v[52:55], v[148:151], v[182:185], v[52:55]
	v_mfma_f32_16x16x32_bf16 v[48:51], v[166:169], v[182:185], v[48:51]
	v_mfma_f32_16x16x32_bf16 v[44:47], v[148:151], v[204:207], v[44:47]
	v_mfma_f32_16x16x32_bf16 v[40:43], v[166:169], v[204:207], v[40:43]
	v_mfma_f32_16x16x32_bf16 v[36:39], v[148:151], v[214:217], v[36:39]
	v_mfma_f32_16x16x32_bf16 v[32:35], v[166:169], v[214:217], v[32:35]
	s_setprio 0
	s_barrier
	s_add_i32 s56, s56, s39
	s_add_u32 s62, s24, s92
	s_addc_u32 s63, s25, s93
	s_mov_b32 m0, s56
	ds_read_b128 v[170:173], v213 offset:16384
	ds_read_b128 v[174:177], v213 offset:17408
	ds_read_b128 v[178:181], v213 offset:18432
	ds_read_b128 v[182:185], v213 offset:19456
	ds_read_b128 v[186:189], v213 offset:20480
	ds_read_b128 v[204:207], v213 offset:21504
	ds_read_b128 v[208:211], v213 offset:22528
	ds_read_b128 v[214:217], v213 offset:23552
	global_load_lds_dwordx4 v192, s[24:25]
	s_add_i32 m0, s56, 0x2000
	s_add_u32 s56, s24, 0x20000
	s_addc_u32 s57, s25, 0
	s_add_i32 s58, s58, s39
	global_load_lds_dwordx4 v156, s[24:25]
	s_mov_b32 m0, s58
	s_nop 0
	global_load_lds_dwordx4 v192, s[56:57]
	s_add_i32 m0, s58, 0x2000
	s_nop 0
	global_load_lds_dwordx4 v156, s[56:57]
	s_add_u32 s64, s26, s92
	s_addc_u32 s65, s27, s93
	s_mov_b32 m0, s21
	s_nop 0
	global_load_lds_dwordx4 v160, s[26:27]
	s_mov_b32 m0, s45
	s_nop 0
	global_load_lds_dwordx4 v158, s[26:27]
	s_waitcnt vmcnt(8)
	s_waitcnt lgkmcnt(0)
	s_barrier
; #define PG8_STAGE(bufoff, gbase, voff) do { _Pragma("unroll") for (int _i = 0; _i < 2; ++_i) \
;         __builtin_amdgcn_global_load_lds((const unsigned*)((const char*)(gbase) + (voff)[_i]), (LAS unsigned*)(lds + (bufoff) + ldsw + _i * 8192), 16, 0, 0); } while (0)
; #define PG8_LDA(dst, b, h) do { _Pragma("unroll") for (int m = 0; m < 4; ++m) _Pragma("unroll") for (int k = 0; k < 2; ++k) dst[m][k] = *(const LAS bf16x8*)(lds + PG8_SA(b, h) + aoff + m * 2048 + k * 1024); } while (0)
; #define PG8_LDB(dst, b, h) do { _Pragma("unroll") for (int n = 0; n < 2; ++n) _Pragma("unroll") for (int k = 0; k < 2; ++k) dst[n][k] = *(const LAS bf16x8*)(lds + PG8_SB(b, h) + boff + n * 2048 + k * 1024); } while (0)
; #define PG8_MMA(ai, bj, At, Bt) do { __builtin_amdgcn_s_setprio(1); _Pragma("unroll") for (int m = 0; m < 4; ++m) _Pragma("unroll") for (int n = 0; n < 2; ++n) _Pragma("unroll") for (int k = 0; k < 2; ++k) \
;         acc[ai][bj][m][n] = __builtin_amdgcn_mfma_f32_16x16x32_bf16(Bt[n][k], At[m][k], acc[ai][bj][m][n], 0, 0, 0); __builtin_amdgcn_s_setprio(0); } while (0)
; #define PG8_WAIT_V(n) asm volatile("s_waitcnt vmcnt(" #n ")" ::: "memory")
; #define PG8_WAIT_L(n) asm volatile("s_waitcnt lgkmcnt(" #n ")" ::: "memory")
; #define PG8_BAR __builtin_amdgcn_s_barrier()
; #define PG8_SCHED __builtin_amdgcn_sched_barrier(0)
; template <class EpiT, class Sched>
; __device__ __forceinline__ void gemm_phase(LAS unsigned char* lds, const Gemm g, const Sched& S, const EpiT& E, int wv) {
;     ...
;             PG8_WAIT_V(8); PG8_WAIT_L(0); PG8_BAR; PG8_MMA(1, 0, At, B0); PG8_MMA(1, 1, At, B1); PG8_BAR; PG8_SCHED;
;             PG8_LDB(B0, 1, 0); PG8_LDB(B1, 1, 1); PG8_SCHED; PG8_LDA(At, 1, 0); PG8_STAGE(PG8_SA(0, 1), a2 + hstepA, voffA);
;             PG8_WAIT_V(8); PG8_WAIT_L(0); PG8_BAR; PG8_MMA(0, 0, At, B0); PG8_MMA(0, 1, At, B1); PG8_BAR; PG8_SCHED;
;             PG8_LDA(At, 1, 1); PG8_STAGE(PG8_SB(1, 0), b3, voffB); PG8_STAGE(PG8_SB(1, 1), b3 + hstepB, voffB); PG8_STAGE(PG8_SA(1, 0), a3, voffA);
	s_setprio 1
	s_waitcnt lgkmcnt(0)
	v_mfma_f32_16x16x32_bf16 v[92:95], v[128:131], v[170:173], v[92:95]
	v_mfma_f32_16x16x32_bf16 v[88:91], v[136:139], v[170:173], v[88:91]
	v_mfma_f32_16x16x32_bf16 v[84:87], v[128:131], v[178:181], v[84:87]
	v_mfma_f32_16x16x32_bf16 v[80:83], v[136:139], v[178:181], v[80:83]
	v_mfma_f32_16x16x32_bf16 v[76:79], v[128:131], v[186:189], v[76:79]
	v_mfma_f32_16x16x32_bf16 v[72:75], v[136:139], v[186:189], v[72:75]
	v_mfma_f32_16x16x32_bf16 v[68:71], v[128:131], v[208:211], v[68:71]
	v_mfma_f32_16x16x32_bf16 v[64:67], v[136:139], v[208:211], v[64:67]
	v_mfma_f32_16x16x32_bf16 v[92:95], v[132:135], v[174:177], v[92:95]
	v_mfma_f32_16x16x32_bf16 v[88:91], v[140:143], v[174:177], v[88:91]
	v_mfma_f32_16x16x32_bf16 v[84:87], v[132:135], v[182:185], v[84:87]
	v_mfma_f32_16x16x32_bf16 v[80:83], v[140:143], v[182:185], v[80:83]
	v_mfma_f32_16x16x32_bf16 v[76:79], v[132:135], v[204:207], v[76:79]
	v_mfma_f32_16x16x32_bf16 v[72:75], v[140:143], v[204:207], v[72:75]
	v_mfma_f32_16x16x32_bf16 v[68:71], v[132:135], v[214:217], v[68:71]
	v_mfma_f32_16x16x32_bf16 v[64:67], v[140:143], v[214:217], v[64:67]
	s_setprio 0
	s_setprio 1
	v_mfma_f32_16x16x32_bf16 v[28:31], v[144:147], v[170:173], v[28:31]
	v_mfma_f32_16x16x32_bf16 v[24:27], v[152:155], v[170:173], v[24:27]
	v_mfma_f32_16x16x32_bf16 v[20:23], v[144:147], v[178:181], v[20:23]
	v_mfma_f32_16x16x32_bf16 v[16:19], v[152:155], v[178:181], v[16:19]
	v_mfma_f32_16x16x32_bf16 v[12:15], v[144:147], v[186:189], v[12:15]
	v_mfma_f32_16x16x32_bf16 v[8:11], v[152:155], v[186:189], v[8:11]
	v_mfma_f32_16x16x32_bf16 v[4:7], v[144:147], v[208:211], v[4:7]
	v_mfma_f32_16x16x32_bf16 v[0:3], v[152:155], v[208:211], v[0:3]
	v_mfma_f32_16x16x32_bf16 v[28:31], v[148:151], v[174:177], v[28:31]
	v_mfma_f32_16x16x32_bf16 v[24:27], v[166:169], v[174:177], v[24:27]
	v_mfma_f32_16x16x32_bf16 v[20:23], v[148:151], v[182:185], v[20:23]
	v_mfma_f32_16x16x32_bf16 v[16:19], v[166:169], v[182:185], v[16:19]
	v_mfma_f32_16x16x32_bf16 v[12:15], v[148:151], v[204:207], v[12:15]
	v_mfma_f32_16x16x32_bf16 v[8:11], v[166:169], v[204:207], v[8:11]
	v_mfma_f32_16x16x32_bf16 v[4:7], v[148:151], v[214:217], v[4:7]
	v_mfma_f32_16x16x32_bf16 v[0:3], v[166:169], v[214:217], v[0:3]
	s_setprio 0
	s_barrier
	s_add_i32 s56, 0, 0x18000
	s_add_i32 s57, 0, 0x1c000
	v_add_u32_e32 v140, s56, v212
	v_add_u32_e32 v166, s57, v212
	ds_read_b128 v[128:131], v140
	ds_read_b128 v[132:135], v140 offset:1024
	ds_read_b128 v[136:139], v140 offset:2048
	ds_read_b128 v[140:143], v140 offset:3072
	ds_read_b128 v[144:147], v166
	ds_read_b128 v[148:151], v166 offset:1024
	ds_read_b128 v[152:155], v166 offset:2048
	ds_read_b128 v[166:169], v166 offset:3072
	s_add_u32 s26, s26, 0x80000
	s_addc_u32 s27, s27, 0
	s_mov_b32 m0, s46
	ds_read_b128 v[170:173], v213 offset:32768
	ds_read_b128 v[174:177], v213 offset:33792
	ds_read_b128 v[178:181], v213 offset:34816
	ds_read_b128 v[182:185], v213 offset:35840
	ds_read_b128 v[186:189], v213 offset:36864
	ds_read_b128 v[204:207], v213 offset:37888
	ds_read_b128 v[208:211], v213 offset:38912
	ds_read_b128 v[214:217], v213 offset:39936
	global_load_lds_dwordx4 v160, s[26:27]
	s_mov_b32 m0, s47
	s_nop 0
	global_load_lds_dwordx4 v158, s[26:27]
	s_waitcnt vmcnt(8)
	s_waitcnt lgkmcnt(0)
	s_barrier
	s_setprio 1
	s_waitcnt lgkmcnt(0)
	v_mfma_f32_16x16x32_bf16 v[124:127], v[128:131], v[170:173], v[124:127]
	v_mfma_f32_16x16x32_bf16 v[120:123], v[136:139], v[170:173], v[120:123]
	v_mfma_f32_16x16x32_bf16 v[116:119], v[128:131], v[178:181], v[116:119]
	v_mfma_f32_16x16x32_bf16 v[112:115], v[136:139], v[178:181], v[112:115]
	v_mfma_f32_16x16x32_bf16 v[108:111], v[128:131], v[186:189], v[108:111]
	v_mfma_f32_16x16x32_bf16 v[104:107], v[136:139], v[186:189], v[104:107]
	v_mfma_f32_16x16x32_bf16 v[100:103], v[128:131], v[208:211], v[100:103]
	v_mfma_f32_16x16x32_bf16 v[96:99], v[136:139], v[208:211], v[96:99]
	v_mfma_f32_16x16x32_bf16 v[124:127], v[132:135], v[174:177], v[124:127]
	v_mfma_f32_16x16x32_bf16 v[120:123], v[140:143], v[174:177], v[120:123]
	v_mfma_f32_16x16x32_bf16 v[116:119], v[132:135], v[182:185], v[116:119]
	v_mfma_f32_16x16x32_bf16 v[112:115], v[140:143], v[182:185], v[112:115]
	v_mfma_f32_16x16x32_bf16 v[108:111], v[132:135], v[204:207], v[108:111]
	v_mfma_f32_16x16x32_bf16 v[104:107], v[140:143], v[204:207], v[104:107]
	v_mfma_f32_16x16x32_bf16 v[100:103], v[132:135], v[214:217], v[100:103]
	v_mfma_f32_16x16x32_bf16 v[96:99], v[140:143], v[214:217], v[96:99]
	s_setprio 0
	s_setprio 1
	v_mfma_f32_16x16x32_bf16 v[60:63], v[144:147], v[170:173], v[60:63]
	v_mfma_f32_16x16x32_bf16 v[56:59], v[152:155], v[170:173], v[56:59]
	v_mfma_f32_16x16x32_bf16 v[52:55], v[144:147], v[178:181], v[52:55]
	v_mfma_f32_16x16x32_bf16 v[48:51], v[152:155], v[178:181], v[48:51]
	v_mfma_f32_16x16x32_bf16 v[44:47], v[144:147], v[186:189], v[44:47]
	v_mfma_f32_16x16x32_bf16 v[40:43], v[152:155], v[186:189], v[40:43]
	v_mfma_f32_16x16x32_bf16 v[36:39], v[144:147], v[208:211], v[36:39]
	v_mfma_f32_16x16x32_bf16 v[32:35], v[152:155], v[208:211], v[32:35]
	v_mfma_f32_16x16x32_bf16 v[60:63], v[148:151], v[174:177], v[60:63]
	v_mfma_f32_16x16x32_bf16 v[56:59], v[166:169], v[174:177], v[56:59]
	v_mfma_f32_16x16x32_bf16 v[52:55], v[148:151], v[182:185], v[52:55]
	v_mfma_f32_16x16x32_bf16 v[48:51], v[166:169], v[182:185], v[48:51]
	v_mfma_f32_16x16x32_bf16 v[44:47], v[148:151], v[204:207], v[44:47]
	v_mfma_f32_16x16x32_bf16 v[40:43], v[166:169], v[204:207], v[40:43]
	v_mfma_f32_16x16x32_bf16 v[36:39], v[148:151], v[214:217], v[36:39]
	v_mfma_f32_16x16x32_bf16 v[32:35], v[166:169], v[214:217], v[32:35]
	s_setprio 0
	s_barrier
; #define PG8_STAGE(bufoff, gbase, voff) do { _Pragma("unroll") for (int _i = 0; _i < 2; ++_i) \
;         __builtin_amdgcn_global_load_lds((const unsigned*)((const char*)(gbase) + (voff)[_i]), (LAS unsigned*)(lds + (bufoff) + ldsw + _i * 8192), 16, 0, 0); } while (0)
; #define PG8_LDA(dst, b, h) do { _Pragma("unroll") for (int m = 0; m < 4; ++m) _Pragma("unroll") for (int k = 0; k < 2; ++k) dst[m][k] = *(const LAS bf16x8*)(lds + PG8_SA(b, h) + aoff + m * 2048 + k * 1024); } while (0)
; #define PG8_MMA(ai, bj, At, Bt) do { __builtin_amdgcn_s_setprio(1); _Pragma("unroll") for (int m = 0; m < 4; ++m) _Pragma("unroll") for (int n = 0; n < 2; ++n) _Pragma("unroll") for (int k = 0; k < 2; ++k) \
;         acc[ai][bj][m][n] = __builtin_amdgcn_mfma_f32_16x16x32_bf16(Bt[n][k], At[m][k], acc[ai][bj][m][n], 0, 0, 0); __builtin_amdgcn_s_setprio(0); } while (0)
; #define PG8_WAIT_V(n) asm volatile("s_waitcnt vmcnt(" #n ")" ::: "memory")
; #define PG8_WAIT_L(n) asm volatile("s_waitcnt lgkmcnt(" #n ")" ::: "memory")
; #define PG8_BAR __builtin_amdgcn_s_barrier()
; #define PG8_SCHED __builtin_amdgcn_sched_barrier(0)
; template <class EpiT, class Sched>
; __device__ __forceinline__ void gemm_phase(LAS unsigned char* lds, const Gemm g, const Sched& S, const EpiT& E, int wv) {
;     ...
;             PG8_LDA(At, 1, 1); PG8_STAGE(PG8_SB(1, 0), b3, voffB); PG8_STAGE(PG8_SB(1, 1), b3 + hstepB, voffB); PG8_STAGE(PG8_SA(1, 0), a3, voffA);
;             PG8_WAIT_V(8); PG8_WAIT_L(0); PG8_BAR; PG8_MMA(1, 0, At, B0); PG8_MMA(1, 1, At, B1); PG8_BAR; PG8_SCHED;
;         }
	s_add_i32 s26, s56, s39
	s_mov_b32 m0, s26
	ds_read_b128 v[170:173], v213 offset:49152
	ds_read_b128 v[174:177], v213 offset:50176
	ds_read_b128 v[178:181], v213 offset:51200
	ds_read_b128 v[182:185], v213 offset:52224
	ds_read_b128 v[186:189], v213 offset:53248
	ds_read_b128 v[204:207], v213 offset:54272
	ds_read_b128 v[208:211], v213 offset:55296
	ds_read_b128 v[214:217], v213 offset:56320
	global_load_lds_dwordx4 v192, s[62:63]
	s_add_i32 m0, s26, 0x2000
	s_add_u32 s24, s24, 0x20080
	s_addc_u32 s25, s25, 0
	s_add_i32 s26, s57, s39
	global_load_lds_dwordx4 v156, s[62:63]
	s_mov_b32 m0, s26
	s_nop 0
	global_load_lds_dwordx4 v192, s[24:25]
	s_add_i32 m0, s26, 0x2000
	s_nop 0
	global_load_lds_dwordx4 v156, s[24:25]
	s_mov_b32 m0, s48
	s_nop 0
	global_load_lds_dwordx4 v160, s[64:65]
	s_mov_b32 m0, s49
	s_nop 0
	global_load_lds_dwordx4 v158, s[64:65]
	s_waitcnt vmcnt(8)
	s_waitcnt lgkmcnt(0)
	s_barrier
	s_setprio 1
	s_waitcnt lgkmcnt(0)
	v_mfma_f32_16x16x32_bf16 v[92:95], v[128:131], v[170:173], v[92:95]
	v_mfma_f32_16x16x32_bf16 v[88:91], v[136:139], v[170:173], v[88:91]
	v_mfma_f32_16x16x32_bf16 v[84:87], v[128:131], v[178:181], v[84:87]
	v_mfma_f32_16x16x32_bf16 v[80:83], v[136:139], v[178:181], v[80:83]
	v_mfma_f32_16x16x32_bf16 v[76:79], v[128:131], v[186:189], v[76:79]
	v_mfma_f32_16x16x32_bf16 v[72:75], v[136:139], v[186:189], v[72:75]
	v_mfma_f32_16x16x32_bf16 v[68:71], v[128:131], v[208:211], v[68:71]
	v_mfma_f32_16x16x32_bf16 v[64:67], v[136:139], v[208:211], v[64:67]
	v_mfma_f32_16x16x32_bf16 v[92:95], v[132:135], v[174:177], v[92:95]
	v_mfma_f32_16x16x32_bf16 v[88:91], v[140:143], v[174:177], v[88:91]
	v_mfma_f32_16x16x32_bf16 v[84:87], v[132:135], v[182:185], v[84:87]
	v_mfma_f32_16x16x32_bf16 v[80:83], v[140:143], v[182:185], v[80:83]
	v_mfma_f32_16x16x32_bf16 v[76:79], v[132:135], v[204:207], v[76:79]
	v_mfma_f32_16x16x32_bf16 v[72:75], v[140:143], v[204:207], v[72:75]
	v_mfma_f32_16x16x32_bf16 v[68:71], v[132:135], v[214:217], v[68:71]
	v_mfma_f32_16x16x32_bf16 v[64:67], v[140:143], v[214:217], v[64:67]
	s_setprio 0
	s_setprio 1
	v_mfma_f32_16x16x32_bf16 v[28:31], v[144:147], v[170:173], v[28:31]
	v_mfma_f32_16x16x32_bf16 v[24:27], v[152:155], v[170:173], v[24:27]
	v_mfma_f32_16x16x32_bf16 v[20:23], v[144:147], v[178:181], v[20:23]
	v_mfma_f32_16x16x32_bf16 v[16:19], v[152:155], v[178:181], v[16:19]
	v_mfma_f32_16x16x32_bf16 v[12:15], v[144:147], v[186:189], v[12:15]
	v_mfma_f32_16x16x32_bf16 v[8:11], v[152:155], v[186:189], v[8:11]
	v_mfma_f32_16x16x32_bf16 v[4:7], v[144:147], v[208:211], v[4:7]
	v_mfma_f32_16x16x32_bf16 v[0:3], v[152:155], v[208:211], v[0:3]
	v_mfma_f32_16x16x32_bf16 v[28:31], v[148:151], v[174:177], v[28:31]
	v_mfma_f32_16x16x32_bf16 v[24:27], v[166:169], v[174:177], v[24:27]
	v_mfma_f32_16x16x32_bf16 v[20:23], v[148:151], v[182:185], v[20:23]
	v_mfma_f32_16x16x32_bf16 v[16:19], v[166:169], v[182:185], v[16:19]
	v_mfma_f32_16x16x32_bf16 v[12:15], v[148:151], v[204:207], v[12:15]
	v_mfma_f32_16x16x32_bf16 v[8:11], v[166:169], v[204:207], v[8:11]
	v_mfma_f32_16x16x32_bf16 v[4:7], v[148:151], v[214:217], v[4:7]
	v_mfma_f32_16x16x32_bf16 v[0:3], v[166:169], v[214:217], v[0:3]
	s_setprio 0
	s_barrier
	s_add_i32 s55, s55, 2
	s_add_u32 s22, s22, 0x100
	s_addc_u32 s23, s23, 0
	s_add_u32 s53, s53, 0x100
	s_addc_u32 s54, s54, 0
	s_cmp_gt_u32 s55, 5
	s_cbranch_scc0 .LBB0_1042
	s_and_b64 vcc, exec, s[10:11]
	s_cbranch_vccz .LBB0_1045
	s_barrier

; #define PG8_STAGE(bufoff, gbase, voff) do { _Pragma("unroll") for (int _i = 0; _i < 2; ++_i) \
;         __builtin_amdgcn_global_load_lds((const unsigned*)((const char*)(gbase) + (voff)[_i]), (LAS unsigned*)(lds + (bufoff) + ldsw + _i * 8192), 16, 0, 0); } while (0)
; #define PG8_LDA(dst, b, h) do { _Pragma("unroll") for (int m = 0; m < 4; ++m) _Pragma("unroll") for (int k = 0; k < 2; ++k) dst[m][k] = *(const LAS bf16x8*)(lds + PG8_SA(b, h) + aoff + m * 2048 + k * 1024); } while (0)
; #define PG8_LDB(dst, b, h) do { _Pragma("unroll") for (int n = 0; n < 2; ++n) _Pragma("unroll") for (int k = 0; k < 2; ++k) dst[n][k] = *(const LAS bf16x8*)(lds + PG8_SB(b, h) + boff + n * 2048 + k * 1024); } while (0)
; #define PG8_MMA(ai, bj, At, Bt) do { __builtin_amdgcn_s_setprio(1); _Pragma("unroll") for (int m = 0; m < 4; ++m) _Pragma("unroll") for (int n = 0; n < 2; ++n) _Pragma("unroll") for (int k = 0; k < 2; ++k) \
;         acc[ai][bj][m][n] = __builtin_amdgcn_mfma_f32_16x16x32_bf16(Bt[n][k], At[m][k], acc[ai][bj][m][n], 0, 0, 0); __builtin_amdgcn_s_setprio(0); } while (0)
; #define PG8_WAIT_V(n) asm volatile("s_waitcnt vmcnt(" #n ")" ::: "memory")
; #define PG8_WAIT_L(n) asm volatile("s_waitcnt lgkmcnt(" #n ")" ::: "memory")
; #define PG8_BAR __builtin_amdgcn_s_barrier()
; #define PG8_SCHED __builtin_amdgcn_sched_barrier(0)
; template <class EpiT, class Sched>
; __device__ __forceinline__ void gemm_phase(LAS unsigned char* lds, const Gemm g, const Sched& S, const EpiT& E, int wv) {
;     ...
;         for (int t = 0; t < nt; t += 2) {
;             const bool last = (t == nt - 2);
;             const char* a1 = cA + (size_t)(t + 1) * kstep;
;             const char* a2 = last ? nA : cA + (size_t)(t + 2) * kstep; const char* b2 = last ? nB : cB + (size_t)(t + 2) * kstep;
;             const char* a3 = a2 + kstep; const char* b3 = b2 + kstep;
;             PG8_LDB(B0, 0, 0); PG8_LDB(B1, 0, 1); PG8_SCHED; PG8_LDA(At, 0, 0); PG8_STAGE(PG8_SA(1, 1), a1 + hstepA, voffA);
;             PG8_WAIT_V(8); PG8_WAIT_L(0); PG8_BAR; PG8_MMA(0, 0, At, B0); PG8_MMA(0, 1, At, B1); PG8_BAR; PG8_SCHED;
;             PG8_LDA(At, 0, 1); PG8_STAGE(PG8_SB(0, 0), b2, voffB); PG8_STAGE(PG8_SB(0, 1), b2 + hstepB, voffB); PG8_STAGE(PG8_SA(0, 0), a2, voffA);
;             PG8_WAIT_V(8); PG8_WAIT_L(0); PG8_BAR; PG8_MMA(1, 0, At, B0); PG8_MMA(1, 1, At, B1); PG8_BAR; PG8_SCHED;
.LBB0_1154:
	s_add_u32 s38, s4, 0xfffc0080
	s_addc_u32 s39, s5, -1
	s_add_i32 s90, 0, 0x10000
	s_cmp_eq_u32 s89, 12
	s_cselect_b32 s41, s1, s39
	s_cselect_b32 s40, s25, s38
	s_cselect_b32 s39, s23, s65
	s_cselect_b32 s38, s33, s64
	s_add_i32 vcc_lo, 0, 0x14000
	v_add_u32_e32 v140, s90, v240
	v_add_u32_e32 v156, vcc_lo, v240
	ds_read_b128 v[120:123], v140
	ds_read_b128 v[124:127], v140 offset:1024
	ds_read_b128 v[136:139], v140 offset:2048
	ds_read_b128 v[140:143], v140 offset:3072
	ds_read_b128 v[144:147], v156
	ds_read_b128 v[148:151], v156 offset:1024
	ds_read_b128 v[152:155], v156 offset:2048
	ds_read_b128 v[156:159], v156 offset:3072
	s_add_i32 m0, s27, 0xc000
	ds_read_b128 v[160:163], v241
	ds_read_b128 v[164:167], v241 offset:1024
	ds_read_b128 v[178:181], v241 offset:2048
	ds_read_b128 v[182:185], v241 offset:3072
	ds_read_b128 v[186:189], v241 offset:4096
	ds_read_b128 v[204:207], v241 offset:5120
	ds_read_b128 v[208:211], v241 offset:6144
	ds_read_b128 v[212:215], v241 offset:7168
	global_load_lds_dwordx4 v174, s[4:5]
	s_add_i32 m0, s27, 0xe000
	s_nop 0
	global_load_lds_dwordx4 v176, s[4:5]
	s_waitcnt vmcnt(8)
	s_waitcnt lgkmcnt(0)
	s_barrier
	s_setprio 1
	s_waitcnt lgkmcnt(0)
	v_mfma_f32_16x16x32_bf16 v[132:135], v[120:123], v[160:163], v[132:135]
	v_mfma_f32_16x16x32_bf16 v[128:131], v[136:139], v[160:163], v[128:131]
	v_mfma_f32_16x16x32_bf16 v[116:119], v[120:123], v[178:181], v[116:119]
	v_mfma_f32_16x16x32_bf16 v[112:115], v[136:139], v[178:181], v[112:115]
	v_mfma_f32_16x16x32_bf16 v[108:111], v[120:123], v[186:189], v[108:111]
	v_mfma_f32_16x16x32_bf16 v[104:107], v[136:139], v[186:189], v[104:107]
	v_mfma_f32_16x16x32_bf16 v[100:103], v[120:123], v[208:211], v[100:103]
	v_mfma_f32_16x16x32_bf16 v[96:99], v[136:139], v[208:211], v[96:99]
	v_mfma_f32_16x16x32_bf16 v[132:135], v[124:127], v[164:167], v[132:135]
	v_mfma_f32_16x16x32_bf16 v[128:131], v[140:143], v[164:167], v[128:131]
	v_mfma_f32_16x16x32_bf16 v[116:119], v[124:127], v[182:185], v[116:119]
	v_mfma_f32_16x16x32_bf16 v[112:115], v[140:143], v[182:185], v[112:115]
	v_mfma_f32_16x16x32_bf16 v[108:111], v[124:127], v[204:207], v[108:111]
	v_mfma_f32_16x16x32_bf16 v[104:107], v[140:143], v[204:207], v[104:107]
	v_mfma_f32_16x16x32_bf16 v[100:103], v[124:127], v[212:215], v[100:103]
	v_mfma_f32_16x16x32_bf16 v[96:99], v[140:143], v[212:215], v[96:99]
	s_setprio 0
	s_setprio 1
	v_mfma_f32_16x16x32_bf16 v[60:63], v[144:147], v[160:163], v[60:63]
	v_mfma_f32_16x16x32_bf16 v[56:59], v[152:155], v[160:163], v[56:59]
	v_mfma_f32_16x16x32_bf16 v[52:55], v[144:147], v[178:181], v[52:55]
	v_mfma_f32_16x16x32_bf16 v[48:51], v[152:155], v[178:181], v[48:51]
	v_mfma_f32_16x16x32_bf16 v[44:47], v[144:147], v[186:189], v[44:47]
	v_mfma_f32_16x16x32_bf16 v[40:43], v[152:155], v[186:189], v[40:43]
	v_mfma_f32_16x16x32_bf16 v[36:39], v[144:147], v[208:211], v[36:39]
	v_mfma_f32_16x16x32_bf16 v[32:35], v[152:155], v[208:211], v[32:35]
	v_mfma_f32_16x16x32_bf16 v[60:63], v[148:151], v[164:167], v[60:63]
	v_mfma_f32_16x16x32_bf16 v[56:59], v[156:159], v[164:167], v[56:59]
	v_mfma_f32_16x16x32_bf16 v[52:55], v[148:151], v[182:185], v[52:55]
	v_mfma_f32_16x16x32_bf16 v[48:51], v[156:159], v[182:185], v[48:51]
	v_mfma_f32_16x16x32_bf16 v[44:47], v[148:151], v[204:207], v[44:47]
	v_mfma_f32_16x16x32_bf16 v[40:43], v[156:159], v[204:207], v[40:43]
	v_mfma_f32_16x16x32_bf16 v[36:39], v[148:151], v[212:215], v[36:39]
	v_mfma_f32_16x16x32_bf16 v[32:35], v[156:159], v[212:215], v[32:35]
	s_setprio 0
	s_barrier
	s_add_i32 s90, s90, s48
	s_add_u32 s36, s38, s92
	s_addc_u32 s37, s39, s93
	s_mov_b32 m0, s90
	ds_read_b128 v[160:163], v241 offset:16384
	ds_read_b128 v[164:167], v241 offset:17408
	ds_read_b128 v[178:181], v241 offset:18432
	ds_read_b128 v[182:185], v241 offset:19456
	ds_read_b128 v[186:189], v241 offset:20480
	ds_read_b128 v[204:207], v241 offset:21504
	ds_read_b128 v[208:211], v241 offset:22528
	ds_read_b128 v[212:215], v241 offset:23552
	global_load_lds_dwordx4 v192, s[38:39]
	s_add_i32 m0, s90, 0x2000
	s_add_u32 s90, s38, 0x100000
	s_addc_u32 s91, s39, 0
	s_add_i32 vcc_lo, vcc_lo, s48
	global_load_lds_dwordx4 v172, s[38:39]
	s_mov_b32 m0, vcc_lo
	s_nop 0
	global_load_lds_dwordx4 v192, s[90:91]
	s_add_i32 m0, vcc_lo, 0x2000
	s_nop 0
	global_load_lds_dwordx4 v172, s[90:91]
	s_add_u32 s98, s40, s92
	s_addc_u32 s99, s41, s93
	s_mov_b32 m0, s27
	s_nop 0
	global_load_lds_dwordx4 v168, s[40:41]
	s_mov_b32 m0, s53
	s_nop 0
	global_load_lds_dwordx4 v170, s[40:41]
	s_waitcnt vmcnt(8)
	s_waitcnt lgkmcnt(0)
	s_barrier
; #define PG8_STAGE(bufoff, gbase, voff) do { _Pragma("unroll") for (int _i = 0; _i < 2; ++_i) \
;         __builtin_amdgcn_global_load_lds((const unsigned*)((const char*)(gbase) + (voff)[_i]), (LAS unsigned*)(lds + (bufoff) + ldsw + _i * 8192), 16, 0, 0); } while (0)
; #define PG8_LDA(dst, b, h) do { _Pragma("unroll") for (int m = 0; m < 4; ++m) _Pragma("unroll") for (int k = 0; k < 2; ++k) dst[m][k] = *(const LAS bf16x8*)(lds + PG8_SA(b, h) + aoff + m * 2048 + k * 1024); } while (0)
; #define PG8_LDB(dst, b, h) do { _Pragma("unroll") for (int n = 0; n < 2; ++n) _Pragma("unroll") for (int k = 0; k < 2; ++k) dst[n][k] = *(const LAS bf16x8*)(lds + PG8_SB(b, h) + boff + n * 2048 + k * 1024); } while (0)
; #define PG8_MMA(ai, bj, At, Bt) do { __builtin_amdgcn_s_setprio(1); _Pragma("unroll") for (int m = 0; m < 4; ++m) _Pragma("unroll") for (int n = 0; n < 2; ++n) _Pragma("unroll") for (int k = 0; k < 2; ++k) \
;         acc[ai][bj][m][n] = __builtin_amdgcn_mfma_f32_16x16x32_bf16(Bt[n][k], At[m][k], acc[ai][bj][m][n], 0, 0, 0); __builtin_amdgcn_s_setprio(0); } while (0)
; #define PG8_WAIT_V(n) asm volatile("s_waitcnt vmcnt(" #n ")" ::: "memory")
; #define PG8_WAIT_L(n) asm volatile("s_waitcnt lgkmcnt(" #n ")" ::: "memory")
; #define PG8_BAR __builtin_amdgcn_s_barrier()
; #define PG8_SCHED __builtin_amdgcn_sched_barrier(0)
; template <class EpiT, class Sched>
; __device__ __forceinline__ void gemm_phase(LAS unsigned char* lds, const Gemm g, const Sched& S, const EpiT& E, int wv) {
;     ...
;             PG8_WAIT_V(8); PG8_WAIT_L(0); PG8_BAR; PG8_MMA(1, 0, At, B0); PG8_MMA(1, 1, At, B1); PG8_BAR; PG8_SCHED;
;             PG8_LDB(B0, 1, 0); PG8_LDB(B1, 1, 1); PG8_SCHED; PG8_LDA(At, 1, 0); PG8_STAGE(PG8_SA(0, 1), a2 + hstepA, voffA);
;             PG8_WAIT_V(8); PG8_WAIT_L(0); PG8_BAR; PG8_MMA(0, 0, At, B0); PG8_MMA(0, 1, At, B1); PG8_BAR; PG8_SCHED;
;             PG8_LDA(At, 1, 1); PG8_STAGE(PG8_SB(1, 0), b3, voffB); PG8_STAGE(PG8_SB(1, 1), b3 + hstepB, voffB); PG8_STAGE(PG8_SA(1, 0), a3, voffA);
	s_setprio 1
	s_waitcnt lgkmcnt(0)
	v_mfma_f32_16x16x32_bf16 v[92:95], v[120:123], v[160:163], v[92:95]
	v_mfma_f32_16x16x32_bf16 v[88:91], v[136:139], v[160:163], v[88:91]
	v_mfma_f32_16x16x32_bf16 v[84:87], v[120:123], v[178:181], v[84:87]
	v_mfma_f32_16x16x32_bf16 v[80:83], v[136:139], v[178:181], v[80:83]
	v_mfma_f32_16x16x32_bf16 v[76:79], v[120:123], v[186:189], v[76:79]
	v_mfma_f32_16x16x32_bf16 v[72:75], v[136:139], v[186:189], v[72:75]
	v_mfma_f32_16x16x32_bf16 v[68:71], v[120:123], v[208:211], v[68:71]
	v_mfma_f32_16x16x32_bf16 v[64:67], v[136:139], v[208:211], v[64:67]
	v_mfma_f32_16x16x32_bf16 v[92:95], v[124:127], v[164:167], v[92:95]
	v_mfma_f32_16x16x32_bf16 v[88:91], v[140:143], v[164:167], v[88:91]
	v_mfma_f32_16x16x32_bf16 v[84:87], v[124:127], v[182:185], v[84:87]
	v_mfma_f32_16x16x32_bf16 v[80:83], v[140:143], v[182:185], v[80:83]
	v_mfma_f32_16x16x32_bf16 v[76:79], v[124:127], v[204:207], v[76:79]
	v_mfma_f32_16x16x32_bf16 v[72:75], v[140:143], v[204:207], v[72:75]
	v_mfma_f32_16x16x32_bf16 v[68:71], v[124:127], v[212:215], v[68:71]
	v_mfma_f32_16x16x32_bf16 v[64:67], v[140:143], v[212:215], v[64:67]
	s_setprio 0
	s_setprio 1
	v_mfma_f32_16x16x32_bf16 v[28:31], v[144:147], v[160:163], v[28:31]
	v_mfma_f32_16x16x32_bf16 v[24:27], v[152:155], v[160:163], v[24:27]
	v_mfma_f32_16x16x32_bf16 v[20:23], v[144:147], v[178:181], v[20:23]
	v_mfma_f32_16x16x32_bf16 v[16:19], v[152:155], v[178:181], v[16:19]
	v_mfma_f32_16x16x32_bf16 v[12:15], v[144:147], v[186:189], v[12:15]
	v_mfma_f32_16x16x32_bf16 v[8:11], v[152:155], v[186:189], v[8:11]
	v_mfma_f32_16x16x32_bf16 v[4:7], v[144:147], v[208:211], v[4:7]
	v_mfma_f32_16x16x32_bf16 v[0:3], v[152:155], v[208:211], v[0:3]
	v_mfma_f32_16x16x32_bf16 v[28:31], v[148:151], v[164:167], v[28:31]
	v_mfma_f32_16x16x32_bf16 v[24:27], v[156:159], v[164:167], v[24:27]
	v_mfma_f32_16x16x32_bf16 v[20:23], v[148:151], v[182:185], v[20:23]
	v_mfma_f32_16x16x32_bf16 v[16:19], v[156:159], v[182:185], v[16:19]
	v_mfma_f32_16x16x32_bf16 v[12:15], v[148:151], v[204:207], v[12:15]
	v_mfma_f32_16x16x32_bf16 v[8:11], v[156:159], v[204:207], v[8:11]
	v_mfma_f32_16x16x32_bf16 v[4:7], v[148:151], v[212:215], v[4:7]
	v_mfma_f32_16x16x32_bf16 v[0:3], v[156:159], v[212:215], v[0:3]
	s_setprio 0
	s_barrier
	s_add_i32 s90, 0, 0x18000
	s_add_i32 s91, 0, 0x1c000
	v_add_u32_e32 v140, s90, v240
	v_add_u32_e32 v156, s91, v240
	ds_read_b128 v[120:123], v140
	ds_read_b128 v[124:127], v140 offset:1024
	ds_read_b128 v[136:139], v140 offset:2048
	ds_read_b128 v[140:143], v140 offset:3072
	ds_read_b128 v[144:147], v156
	ds_read_b128 v[148:151], v156 offset:1024
	ds_read_b128 v[152:155], v156 offset:2048
	ds_read_b128 v[156:159], v156 offset:3072
	s_add_u32 s40, s40, 0x40000
	s_addc_u32 s41, s41, 0
	s_mov_b32 m0, s54
	ds_read_b128 v[160:163], v241 offset:32768
	ds_read_b128 v[164:167], v241 offset:33792
	ds_read_b128 v[178:181], v241 offset:34816
	ds_read_b128 v[182:185], v241 offset:35840
	ds_read_b128 v[186:189], v241 offset:36864
	ds_read_b128 v[204:207], v241 offset:37888
	ds_read_b128 v[208:211], v241 offset:38912
	ds_read_b128 v[212:215], v241 offset:39936
	global_load_lds_dwordx4 v168, s[40:41]
	s_mov_b32 m0, s55
	s_nop 0
	global_load_lds_dwordx4 v170, s[40:41]
	s_waitcnt vmcnt(8)
	s_waitcnt lgkmcnt(0)
	s_barrier
	s_setprio 1
	s_waitcnt lgkmcnt(0)
	v_mfma_f32_16x16x32_bf16 v[132:135], v[120:123], v[160:163], v[132:135]
	v_mfma_f32_16x16x32_bf16 v[128:131], v[136:139], v[160:163], v[128:131]
	v_mfma_f32_16x16x32_bf16 v[116:119], v[120:123], v[178:181], v[116:119]
	v_mfma_f32_16x16x32_bf16 v[112:115], v[136:139], v[178:181], v[112:115]
	v_mfma_f32_16x16x32_bf16 v[108:111], v[120:123], v[186:189], v[108:111]
	v_mfma_f32_16x16x32_bf16 v[104:107], v[136:139], v[186:189], v[104:107]
	v_mfma_f32_16x16x32_bf16 v[100:103], v[120:123], v[208:211], v[100:103]
	v_mfma_f32_16x16x32_bf16 v[96:99], v[136:139], v[208:211], v[96:99]
	v_mfma_f32_16x16x32_bf16 v[132:135], v[124:127], v[164:167], v[132:135]
	v_mfma_f32_16x16x32_bf16 v[128:131], v[140:143], v[164:167], v[128:131]
	v_mfma_f32_16x16x32_bf16 v[116:119], v[124:127], v[182:185], v[116:119]
	v_mfma_f32_16x16x32_bf16 v[112:115], v[140:143], v[182:185], v[112:115]
	v_mfma_f32_16x16x32_bf16 v[108:111], v[124:127], v[204:207], v[108:111]
	v_mfma_f32_16x16x32_bf16 v[104:107], v[140:143], v[204:207], v[104:107]
	v_mfma_f32_16x16x32_bf16 v[100:103], v[124:127], v[212:215], v[100:103]
	v_mfma_f32_16x16x32_bf16 v[96:99], v[140:143], v[212:215], v[96:99]
	s_setprio 0
	s_setprio 1
	v_mfma_f32_16x16x32_bf16 v[60:63], v[144:147], v[160:163], v[60:63]
	v_mfma_f32_16x16x32_bf16 v[56:59], v[152:155], v[160:163], v[56:59]
	v_mfma_f32_16x16x32_bf16 v[52:55], v[144:147], v[178:181], v[52:55]
	v_mfma_f32_16x16x32_bf16 v[48:51], v[152:155], v[178:181], v[48:51]
	v_mfma_f32_16x16x32_bf16 v[44:47], v[144:147], v[186:189], v[44:47]
	v_mfma_f32_16x16x32_bf16 v[40:43], v[152:155], v[186:189], v[40:43]
	v_mfma_f32_16x16x32_bf16 v[36:39], v[144:147], v[208:211], v[36:39]
	v_mfma_f32_16x16x32_bf16 v[32:35], v[152:155], v[208:211], v[32:35]
	v_mfma_f32_16x16x32_bf16 v[60:63], v[148:151], v[164:167], v[60:63]
	v_mfma_f32_16x16x32_bf16 v[56:59], v[156:159], v[164:167], v[56:59]
	v_mfma_f32_16x16x32_bf16 v[52:55], v[148:151], v[182:185], v[52:55]
	v_mfma_f32_16x16x32_bf16 v[48:51], v[156:159], v[182:185], v[48:51]
	v_mfma_f32_16x16x32_bf16 v[44:47], v[148:151], v[204:207], v[44:47]
	v_mfma_f32_16x16x32_bf16 v[40:43], v[156:159], v[204:207], v[40:43]
	v_mfma_f32_16x16x32_bf16 v[36:39], v[148:151], v[212:215], v[36:39]
	v_mfma_f32_16x16x32_bf16 v[32:35], v[156:159], v[212:215], v[32:35]
	s_setprio 0
	s_barrier
; #define PG8_STAGE(bufoff, gbase, voff) do { _Pragma("unroll") for (int _i = 0; _i < 2; ++_i) \
;         __builtin_amdgcn_global_load_lds((const unsigned*)((const char*)(gbase) + (voff)[_i]), (LAS unsigned*)(lds + (bufoff) + ldsw + _i * 8192), 16, 0, 0); } while (0)
; #define PG8_LDA(dst, b, h) do { _Pragma("unroll") for (int m = 0; m < 4; ++m) _Pragma("unroll") for (int k = 0; k < 2; ++k) dst[m][k] = *(const LAS bf16x8*)(lds + PG8_SA(b, h) + aoff + m * 2048 + k * 1024); } while (0)
; #define PG8_MMA(ai, bj, At, Bt) do { __builtin_amdgcn_s_setprio(1); _Pragma("unroll") for (int m = 0; m < 4; ++m) _Pragma("unroll") for (int n = 0; n < 2; ++n) _Pragma("unroll") for (int k = 0; k < 2; ++k) \
;         acc[ai][bj][m][n] = __builtin_amdgcn_mfma_f32_16x16x32_bf16(Bt[n][k], At[m][k], acc[ai][bj][m][n], 0, 0, 0); __builtin_amdgcn_s_setprio(0); } while (0)
; #define PG8_WAIT_V(n) asm volatile("s_waitcnt vmcnt(" #n ")" ::: "memory")
; #define PG8_WAIT_L(n) asm volatile("s_waitcnt lgkmcnt(" #n ")" ::: "memory")
; #define PG8_BAR __builtin_amdgcn_s_barrier()
; #define PG8_SCHED __builtin_amdgcn_sched_barrier(0)
; template <class EpiT, class Sched>
; __device__ __forceinline__ void gemm_phase(LAS unsigned char* lds, const Gemm g, const Sched& S, const EpiT& E, int wv) {
;     ...
;             PG8_LDA(At, 1, 1); PG8_STAGE(PG8_SB(1, 0), b3, voffB); PG8_STAGE(PG8_SB(1, 1), b3 + hstepB, voffB); PG8_STAGE(PG8_SA(1, 0), a3, voffA);
;             PG8_WAIT_V(8); PG8_WAIT_L(0); PG8_BAR; PG8_MMA(1, 0, At, B0); PG8_MMA(1, 1, At, B1); PG8_BAR; PG8_SCHED;
;         }
	s_add_i32 s40, s90, s48
	s_mov_b32 m0, s40
	ds_read_b128 v[160:163], v241 offset:49152
	ds_read_b128 v[164:167], v241 offset:50176
	ds_read_b128 v[178:181], v241 offset:51200
	ds_read_b128 v[182:185], v241 offset:52224
	ds_read_b128 v[186:189], v241 offset:53248
	ds_read_b128 v[204:207], v241 offset:54272
	ds_read_b128 v[208:211], v241 offset:55296
	ds_read_b128 v[212:215], v241 offset:56320
	global_load_lds_dwordx4 v192, s[36:37]
	s_add_i32 m0, s40, 0x2000
	s_add_u32 s38, s38, 0x100080
	s_addc_u32 s39, s39, 0
	s_add_i32 s40, s91, s48
	global_load_lds_dwordx4 v172, s[36:37]
	s_mov_b32 m0, s40
	s_nop 0
	global_load_lds_dwordx4 v192, s[38:39]
	s_add_i32 m0, s40, 0x2000
	s_nop 0
	global_load_lds_dwordx4 v172, s[38:39]
	s_mov_b32 m0, s62
	s_nop 0
	global_load_lds_dwordx4 v168, s[98:99]
	s_mov_b32 m0, s63
	s_nop 0
	global_load_lds_dwordx4 v170, s[98:99]
	s_waitcnt vmcnt(8)
	s_waitcnt lgkmcnt(0)
	s_barrier
	s_setprio 1
	s_waitcnt lgkmcnt(0)
	v_mfma_f32_16x16x32_bf16 v[92:95], v[120:123], v[160:163], v[92:95]
	v_mfma_f32_16x16x32_bf16 v[88:91], v[136:139], v[160:163], v[88:91]
	v_mfma_f32_16x16x32_bf16 v[84:87], v[120:123], v[178:181], v[84:87]
	v_mfma_f32_16x16x32_bf16 v[80:83], v[136:139], v[178:181], v[80:83]
	v_mfma_f32_16x16x32_bf16 v[76:79], v[120:123], v[186:189], v[76:79]
	v_mfma_f32_16x16x32_bf16 v[72:75], v[136:139], v[186:189], v[72:75]
	v_mfma_f32_16x16x32_bf16 v[68:71], v[120:123], v[208:211], v[68:71]
	v_mfma_f32_16x16x32_bf16 v[64:67], v[136:139], v[208:211], v[64:67]
	v_mfma_f32_16x16x32_bf16 v[92:95], v[124:127], v[164:167], v[92:95]
	v_mfma_f32_16x16x32_bf16 v[88:91], v[140:143], v[164:167], v[88:91]
	v_mfma_f32_16x16x32_bf16 v[84:87], v[124:127], v[182:185], v[84:87]
	v_mfma_f32_16x16x32_bf16 v[80:83], v[140:143], v[182:185], v[80:83]
	v_mfma_f32_16x16x32_bf16 v[76:79], v[124:127], v[204:207], v[76:79]
	v_mfma_f32_16x16x32_bf16 v[72:75], v[140:143], v[204:207], v[72:75]
	v_mfma_f32_16x16x32_bf16 v[68:71], v[124:127], v[212:215], v[68:71]
	v_mfma_f32_16x16x32_bf16 v[64:67], v[140:143], v[212:215], v[64:67]
	s_setprio 0
	s_setprio 1
	v_mfma_f32_16x16x32_bf16 v[28:31], v[144:147], v[160:163], v[28:31]
	v_mfma_f32_16x16x32_bf16 v[24:27], v[152:155], v[160:163], v[24:27]
	v_mfma_f32_16x16x32_bf16 v[20:23], v[144:147], v[178:181], v[20:23]
	v_mfma_f32_16x16x32_bf16 v[16:19], v[152:155], v[178:181], v[16:19]
	v_mfma_f32_16x16x32_bf16 v[12:15], v[144:147], v[186:189], v[12:15]
	v_mfma_f32_16x16x32_bf16 v[8:11], v[152:155], v[186:189], v[8:11]
	v_mfma_f32_16x16x32_bf16 v[4:7], v[144:147], v[208:211], v[4:7]
	v_mfma_f32_16x16x32_bf16 v[0:3], v[152:155], v[208:211], v[0:3]
	v_mfma_f32_16x16x32_bf16 v[28:31], v[148:151], v[164:167], v[28:31]
	v_mfma_f32_16x16x32_bf16 v[24:27], v[156:159], v[164:167], v[24:27]
	v_mfma_f32_16x16x32_bf16 v[20:23], v[148:151], v[182:185], v[20:23]
	v_mfma_f32_16x16x32_bf16 v[16:19], v[156:159], v[182:185], v[16:19]
	v_mfma_f32_16x16x32_bf16 v[12:15], v[148:151], v[204:207], v[12:15]
	v_mfma_f32_16x16x32_bf16 v[8:11], v[156:159], v[204:207], v[8:11]
	v_mfma_f32_16x16x32_bf16 v[4:7], v[148:151], v[212:215], v[4:7]
	v_mfma_f32_16x16x32_bf16 v[0:3], v[156:159], v[212:215], v[0:3]
	s_setprio 0
	s_barrier
	s_add_i32 s89, s89, 2
	s_add_u32 s4, s4, 0x100
	s_addc_u32 s5, s5, 0
	s_add_u32 s64, s64, 0x100
	s_addc_u32 s65, s65, 0
	s_cmp_gt_u32 s89, 13
	s_cbranch_scc0 .LBB0_1154
	s_and_b64 vcc, exec, s[20:21]
	s_cbranch_vccz .LBB0_1157
	s_barrier

; #define PG8_STAGE(bufoff, gbase, voff) do { _Pragma("unroll") for (int _i = 0; _i < 2; ++_i) \
;         __builtin_amdgcn_global_load_lds((const unsigned*)((const char*)(gbase) + (voff)[_i]), (LAS unsigned*)(lds + (bufoff) + ldsw + _i * 8192), 16, 0, 0); } while (0)
; #define PG8_LDA(dst, b, h) do { _Pragma("unroll") for (int m = 0; m < 4; ++m) _Pragma("unroll") for (int k = 0; k < 2; ++k) dst[m][k] = *(const LAS bf16x8*)(lds + PG8_SA(b, h) + aoff + m * 2048 + k * 1024); } while (0)
; #define PG8_LDB(dst, b, h) do { _Pragma("unroll") for (int n = 0; n < 2; ++n) _Pragma("unroll") for (int k = 0; k < 2; ++k) dst[n][k] = *(const LAS bf16x8*)(lds + PG8_SB(b, h) + boff + n * 2048 + k * 1024); } while (0)
; #define PG8_MMA(ai, bj, At, Bt) do { __builtin_amdgcn_s_setprio(1); _Pragma("unroll") for (int m = 0; m < 4; ++m) _Pragma("unroll") for (int n = 0; n < 2; ++n) _Pragma("unroll") for (int k = 0; k < 2; ++k) \
;         acc[ai][bj][m][n] = __builtin_amdgcn_mfma_f32_16x16x32_bf16(Bt[n][k], At[m][k], acc[ai][bj][m][n], 0, 0, 0); __builtin_amdgcn_s_setprio(0); } while (0)
; #define PG8_WAIT_V(n) asm volatile("s_waitcnt vmcnt(" #n ")" ::: "memory")
; #define PG8_WAIT_L(n) asm volatile("s_waitcnt lgkmcnt(" #n ")" ::: "memory")
; #define PG8_BAR __builtin_amdgcn_s_barrier()
; #define PG8_SCHED __builtin_amdgcn_sched_barrier(0)
; template <class EpiT, class Sched>
; __device__ __forceinline__ void gemm_phase(LAS unsigned char* lds, const Gemm g, const Sched& S, const EpiT& E, int wv) {
;     ...
;         for (int t = 0; t < nt; t += 2) {
;             const bool last = (t == nt - 2);
;             const char* a1 = cA + (size_t)(t + 1) * kstep;
;             const char* a2 = last ? nA : cA + (size_t)(t + 2) * kstep; const char* b2 = last ? nB : cB + (size_t)(t + 2) * kstep;
;             const char* a3 = a2 + kstep; const char* b3 = b2 + kstep;
;             PG8_LDB(B0, 0, 0); PG8_LDB(B1, 0, 1); PG8_SCHED; PG8_LDA(At, 0, 0); PG8_STAGE(PG8_SA(1, 1), a1 + hstepA, voffA);
;             PG8_WAIT_V(8); PG8_WAIT_L(0); PG8_BAR; PG8_MMA(0, 0, At, B0); PG8_MMA(0, 1, At, B1); PG8_BAR; PG8_SCHED;
;             PG8_LDA(At, 0, 1); PG8_STAGE(PG8_SB(0, 0), b2, voffB); PG8_STAGE(PG8_SB(0, 1), b2 + hstepB, voffB); PG8_STAGE(PG8_SA(0, 0), a2, voffA);
;             PG8_WAIT_V(8); PG8_WAIT_L(0); PG8_BAR; PG8_MMA(1, 0, At, B0); PG8_MMA(1, 1, At, B1); PG8_BAR; PG8_SCHED;
.LBB0_1271:
	s_add_u32 s24, s22, 0xfffc0080
	s_addc_u32 s25, s23, -1
	s_add_i32 s56, 0, 0x10000
	s_cmp_eq_u32 s55, 12
	s_cselect_b32 s27, s13, s25
	s_cselect_b32 s26, s51, s24
	s_cselect_b32 s25, s11, s54
	s_cselect_b32 s24, s52, s53
	s_add_i32 s58, 0, 0x14000
	v_add_u32_e32 v150, s56, v158
	v_add_u32_e32 v168, s58, v158
	ds_read_b128 v[128:131], v150
	ds_read_b128 v[132:135], v150 offset:1024
	ds_read_b128 v[146:149], v150 offset:2048
	ds_read_b128 v[150:153], v150 offset:3072
	ds_read_b128 v[154:157], v168
	ds_read_b128 v[160:163], v168 offset:1024
	ds_read_b128 v[164:167], v168 offset:2048
	ds_read_b128 v[168:171], v168 offset:3072
	s_add_i32 m0, s19, 0xc000
	ds_read_b128 v[172:175], v159
	ds_read_b128 v[176:179], v159 offset:1024
	ds_read_b128 v[180:183], v159 offset:2048
	ds_read_b128 v[184:187], v159 offset:3072
	ds_read_b128 v[188:191], v159 offset:4096
	ds_read_b128 v[204:207], v159 offset:5120
	ds_read_b128 v[208:211], v159 offset:6144
	ds_read_b128 v[212:215], v159 offset:7168
	global_load_lds_dwordx4 v142, s[22:23]
	s_add_i32 m0, s19, 0xe000
	s_nop 0
	global_load_lds_dwordx4 v144, s[22:23]
	s_waitcnt vmcnt(8)
	s_waitcnt lgkmcnt(0)
	s_barrier
	s_setprio 1
	s_waitcnt lgkmcnt(0)
	v_mfma_f32_16x16x32_bf16 v[124:127], v[128:131], v[172:175], v[124:127]
	v_mfma_f32_16x16x32_bf16 v[120:123], v[146:149], v[172:175], v[120:123]
	v_mfma_f32_16x16x32_bf16 v[116:119], v[128:131], v[180:183], v[116:119]
	v_mfma_f32_16x16x32_bf16 v[112:115], v[146:149], v[180:183], v[112:115]
	v_mfma_f32_16x16x32_bf16 v[108:111], v[128:131], v[188:191], v[108:111]
	v_mfma_f32_16x16x32_bf16 v[104:107], v[146:149], v[188:191], v[104:107]
	v_mfma_f32_16x16x32_bf16 v[100:103], v[128:131], v[208:211], v[100:103]
	v_mfma_f32_16x16x32_bf16 v[96:99], v[146:149], v[208:211], v[96:99]
	v_mfma_f32_16x16x32_bf16 v[124:127], v[132:135], v[176:179], v[124:127]
	v_mfma_f32_16x16x32_bf16 v[120:123], v[150:153], v[176:179], v[120:123]
	v_mfma_f32_16x16x32_bf16 v[116:119], v[132:135], v[184:187], v[116:119]
	v_mfma_f32_16x16x32_bf16 v[112:115], v[150:153], v[184:187], v[112:115]
	v_mfma_f32_16x16x32_bf16 v[108:111], v[132:135], v[204:207], v[108:111]
	v_mfma_f32_16x16x32_bf16 v[104:107], v[150:153], v[204:207], v[104:107]
	v_mfma_f32_16x16x32_bf16 v[100:103], v[132:135], v[212:215], v[100:103]
	v_mfma_f32_16x16x32_bf16 v[96:99], v[150:153], v[212:215], v[96:99]
	s_setprio 0
	s_setprio 1
	v_mfma_f32_16x16x32_bf16 v[68:71], v[154:157], v[172:175], v[68:71]
	v_mfma_f32_16x16x32_bf16 v[64:67], v[164:167], v[172:175], v[64:67]
	v_mfma_f32_16x16x32_bf16 v[52:55], v[154:157], v[180:183], v[52:55]
	v_mfma_f32_16x16x32_bf16 v[48:51], v[164:167], v[180:183], v[48:51]
	v_mfma_f32_16x16x32_bf16 v[44:47], v[154:157], v[188:191], v[44:47]
	v_mfma_f32_16x16x32_bf16 v[40:43], v[164:167], v[188:191], v[40:43]
	v_mfma_f32_16x16x32_bf16 v[36:39], v[154:157], v[208:211], v[36:39]
	v_mfma_f32_16x16x32_bf16 v[32:35], v[164:167], v[208:211], v[32:35]
	v_mfma_f32_16x16x32_bf16 v[68:71], v[160:163], v[176:179], v[68:71]
	v_mfma_f32_16x16x32_bf16 v[64:67], v[168:171], v[176:179], v[64:67]
	v_mfma_f32_16x16x32_bf16 v[52:55], v[160:163], v[184:187], v[52:55]
	v_mfma_f32_16x16x32_bf16 v[48:51], v[168:171], v[184:187], v[48:51]
	v_mfma_f32_16x16x32_bf16 v[44:47], v[160:163], v[204:207], v[44:47]
	v_mfma_f32_16x16x32_bf16 v[40:43], v[168:171], v[204:207], v[40:43]
	v_mfma_f32_16x16x32_bf16 v[36:39], v[160:163], v[212:215], v[36:39]
	v_mfma_f32_16x16x32_bf16 v[32:35], v[168:171], v[212:215], v[32:35]
	s_setprio 0
	s_barrier
	s_add_i32 s56, s56, s33
	s_add_u32 s62, s24, s92
	s_addc_u32 s63, s25, s93
	s_mov_b32 m0, s56
	ds_read_b128 v[172:175], v159 offset:16384
	ds_read_b128 v[176:179], v159 offset:17408
	ds_read_b128 v[180:183], v159 offset:18432
	ds_read_b128 v[184:187], v159 offset:19456
	ds_read_b128 v[188:191], v159 offset:20480
	ds_read_b128 v[204:207], v159 offset:21504
	ds_read_b128 v[208:211], v159 offset:22528
	ds_read_b128 v[212:215], v159 offset:23552
	global_load_lds_dwordx4 v192, s[24:25]
	s_add_i32 m0, s56, 0x2000
	s_add_u32 s56, s24, 0x40000
	s_addc_u32 s57, s25, 0
	s_add_i32 s58, s58, s33
	global_load_lds_dwordx4 v140, s[24:25]
	s_mov_b32 m0, s58
	s_nop 0
	global_load_lds_dwordx4 v192, s[56:57]
	s_add_i32 m0, s58, 0x2000
	s_nop 0
	global_load_lds_dwordx4 v140, s[56:57]
	s_add_u32 s64, s26, s92
	s_addc_u32 s65, s27, s93
	s_mov_b32 m0, s19
	s_nop 0
	global_load_lds_dwordx4 v136, s[26:27]
	s_mov_b32 m0, s21
	s_nop 0
	global_load_lds_dwordx4 v138, s[26:27]
	s_waitcnt vmcnt(8)
	s_waitcnt lgkmcnt(0)
	s_barrier
; #define PG8_STAGE(bufoff, gbase, voff) do { _Pragma("unroll") for (int _i = 0; _i < 2; ++_i) \
;         __builtin_amdgcn_global_load_lds((const unsigned*)((const char*)(gbase) + (voff)[_i]), (LAS unsigned*)(lds + (bufoff) + ldsw + _i * 8192), 16, 0, 0); } while (0)
; #define PG8_LDA(dst, b, h) do { _Pragma("unroll") for (int m = 0; m < 4; ++m) _Pragma("unroll") for (int k = 0; k < 2; ++k) dst[m][k] = *(const LAS bf16x8*)(lds + PG8_SA(b, h) + aoff + m * 2048 + k * 1024); } while (0)
; #define PG8_LDB(dst, b, h) do { _Pragma("unroll") for (int n = 0; n < 2; ++n) _Pragma("unroll") for (int k = 0; k < 2; ++k) dst[n][k] = *(const LAS bf16x8*)(lds + PG8_SB(b, h) + boff + n * 2048 + k * 1024); } while (0)
; #define PG8_MMA(ai, bj, At, Bt) do { __builtin_amdgcn_s_setprio(1); _Pragma("unroll") for (int m = 0; m < 4; ++m) _Pragma("unroll") for (int n = 0; n < 2; ++n) _Pragma("unroll") for (int k = 0; k < 2; ++k) \
;         acc[ai][bj][m][n] = __builtin_amdgcn_mfma_f32_16x16x32_bf16(Bt[n][k], At[m][k], acc[ai][bj][m][n], 0, 0, 0); __builtin_amdgcn_s_setprio(0); } while (0)
; #define PG8_WAIT_V(n) asm volatile("s_waitcnt vmcnt(" #n ")" ::: "memory")
; #define PG8_WAIT_L(n) asm volatile("s_waitcnt lgkmcnt(" #n ")" ::: "memory")
; #define PG8_BAR __builtin_amdgcn_s_barrier()
; #define PG8_SCHED __builtin_amdgcn_sched_barrier(0)
; template <class EpiT, class Sched>
; __device__ __forceinline__ void gemm_phase(LAS unsigned char* lds, const Gemm g, const Sched& S, const EpiT& E, int wv) {
;     ...
;             PG8_WAIT_V(8); PG8_WAIT_L(0); PG8_BAR; PG8_MMA(1, 0, At, B0); PG8_MMA(1, 1, At, B1); PG8_BAR; PG8_SCHED;
;             PG8_LDB(B0, 1, 0); PG8_LDB(B1, 1, 1); PG8_SCHED; PG8_LDA(At, 1, 0); PG8_STAGE(PG8_SA(0, 1), a2 + hstepA, voffA);
;             PG8_WAIT_V(8); PG8_WAIT_L(0); PG8_BAR; PG8_MMA(0, 0, At, B0); PG8_MMA(0, 1, At, B1); PG8_BAR; PG8_SCHED;
;             PG8_LDA(At, 1, 1); PG8_STAGE(PG8_SB(1, 0), b3, voffB); PG8_STAGE(PG8_SB(1, 1), b3 + hstepB, voffB); PG8_STAGE(PG8_SA(1, 0), a3, voffA);
	s_setprio 1
	s_waitcnt lgkmcnt(0)
	v_mfma_f32_16x16x32_bf16 v[92:95], v[128:131], v[172:175], v[92:95]
	v_mfma_f32_16x16x32_bf16 v[88:91], v[146:149], v[172:175], v[88:91]
	v_mfma_f32_16x16x32_bf16 v[84:87], v[128:131], v[180:183], v[84:87]
	v_mfma_f32_16x16x32_bf16 v[80:83], v[146:149], v[180:183], v[80:83]
	v_mfma_f32_16x16x32_bf16 v[76:79], v[128:131], v[188:191], v[76:79]
	v_mfma_f32_16x16x32_bf16 v[72:75], v[146:149], v[188:191], v[72:75]
	v_mfma_f32_16x16x32_bf16 v[60:63], v[128:131], v[208:211], v[60:63]
	v_mfma_f32_16x16x32_bf16 v[56:59], v[146:149], v[208:211], v[56:59]
	v_mfma_f32_16x16x32_bf16 v[92:95], v[132:135], v[176:179], v[92:95]
	v_mfma_f32_16x16x32_bf16 v[88:91], v[150:153], v[176:179], v[88:91]
	v_mfma_f32_16x16x32_bf16 v[84:87], v[132:135], v[184:187], v[84:87]
	v_mfma_f32_16x16x32_bf16 v[80:83], v[150:153], v[184:187], v[80:83]
	v_mfma_f32_16x16x32_bf16 v[76:79], v[132:135], v[204:207], v[76:79]
	v_mfma_f32_16x16x32_bf16 v[72:75], v[150:153], v[204:207], v[72:75]
	v_mfma_f32_16x16x32_bf16 v[60:63], v[132:135], v[212:215], v[60:63]
	v_mfma_f32_16x16x32_bf16 v[56:59], v[150:153], v[212:215], v[56:59]
	s_setprio 0
	s_setprio 1
	v_mfma_f32_16x16x32_bf16 v[28:31], v[154:157], v[172:175], v[28:31]
	v_mfma_f32_16x16x32_bf16 v[24:27], v[164:167], v[172:175], v[24:27]
	v_mfma_f32_16x16x32_bf16 v[20:23], v[154:157], v[180:183], v[20:23]
	v_mfma_f32_16x16x32_bf16 v[16:19], v[164:167], v[180:183], v[16:19]
	v_mfma_f32_16x16x32_bf16 v[12:15], v[154:157], v[188:191], v[12:15]
	v_mfma_f32_16x16x32_bf16 v[8:11], v[164:167], v[188:191], v[8:11]
	v_mfma_f32_16x16x32_bf16 v[4:7], v[154:157], v[208:211], v[4:7]
	v_mfma_f32_16x16x32_bf16 v[0:3], v[164:167], v[208:211], v[0:3]
	v_mfma_f32_16x16x32_bf16 v[28:31], v[160:163], v[176:179], v[28:31]
	v_mfma_f32_16x16x32_bf16 v[24:27], v[168:171], v[176:179], v[24:27]
	v_mfma_f32_16x16x32_bf16 v[20:23], v[160:163], v[184:187], v[20:23]
	v_mfma_f32_16x16x32_bf16 v[16:19], v[168:171], v[184:187], v[16:19]
	v_mfma_f32_16x16x32_bf16 v[12:15], v[160:163], v[204:207], v[12:15]
	v_mfma_f32_16x16x32_bf16 v[8:11], v[168:171], v[204:207], v[8:11]
	v_mfma_f32_16x16x32_bf16 v[4:7], v[160:163], v[212:215], v[4:7]
	v_mfma_f32_16x16x32_bf16 v[0:3], v[168:171], v[212:215], v[0:3]
	s_setprio 0
	s_barrier
	s_add_i32 s56, 0, 0x18000
	s_add_i32 s57, 0, 0x1c000
	v_add_u32_e32 v150, s56, v158
	v_add_u32_e32 v168, s57, v158
	ds_read_b128 v[128:131], v150
	ds_read_b128 v[132:135], v150 offset:1024
	ds_read_b128 v[146:149], v150 offset:2048
	ds_read_b128 v[150:153], v150 offset:3072
	ds_read_b128 v[154:157], v168
	ds_read_b128 v[160:163], v168 offset:1024
	ds_read_b128 v[164:167], v168 offset:2048
	ds_read_b128 v[168:171], v168 offset:3072
	s_add_u32 s26, s26, 0x40000
	s_addc_u32 s27, s27, 0
	s_mov_b32 m0, s38
	ds_read_b128 v[172:175], v159 offset:32768
	ds_read_b128 v[176:179], v159 offset:33792
	ds_read_b128 v[180:183], v159 offset:34816
	ds_read_b128 v[184:187], v159 offset:35840
	ds_read_b128 v[188:191], v159 offset:36864
	ds_read_b128 v[204:207], v159 offset:37888
	ds_read_b128 v[208:211], v159 offset:38912
	ds_read_b128 v[212:215], v159 offset:39936
	global_load_lds_dwordx4 v136, s[26:27]
	s_mov_b32 m0, s39
	s_nop 0
	global_load_lds_dwordx4 v138, s[26:27]
	s_waitcnt vmcnt(8)
	s_waitcnt lgkmcnt(0)
	s_barrier
	s_setprio 1
	s_waitcnt lgkmcnt(0)
	v_mfma_f32_16x16x32_bf16 v[124:127], v[128:131], v[172:175], v[124:127]
	v_mfma_f32_16x16x32_bf16 v[120:123], v[146:149], v[172:175], v[120:123]
	v_mfma_f32_16x16x32_bf16 v[116:119], v[128:131], v[180:183], v[116:119]
	v_mfma_f32_16x16x32_bf16 v[112:115], v[146:149], v[180:183], v[112:115]
	v_mfma_f32_16x16x32_bf16 v[108:111], v[128:131], v[188:191], v[108:111]
	v_mfma_f32_16x16x32_bf16 v[104:107], v[146:149], v[188:191], v[104:107]
	v_mfma_f32_16x16x32_bf16 v[100:103], v[128:131], v[208:211], v[100:103]
	v_mfma_f32_16x16x32_bf16 v[96:99], v[146:149], v[208:211], v[96:99]
	v_mfma_f32_16x16x32_bf16 v[124:127], v[132:135], v[176:179], v[124:127]
	v_mfma_f32_16x16x32_bf16 v[120:123], v[150:153], v[176:179], v[120:123]
	v_mfma_f32_16x16x32_bf16 v[116:119], v[132:135], v[184:187], v[116:119]
	v_mfma_f32_16x16x32_bf16 v[112:115], v[150:153], v[184:187], v[112:115]
	v_mfma_f32_16x16x32_bf16 v[108:111], v[132:135], v[204:207], v[108:111]
	v_mfma_f32_16x16x32_bf16 v[104:107], v[150:153], v[204:207], v[104:107]
	v_mfma_f32_16x16x32_bf16 v[100:103], v[132:135], v[212:215], v[100:103]
	v_mfma_f32_16x16x32_bf16 v[96:99], v[150:153], v[212:215], v[96:99]
	s_setprio 0
	s_setprio 1
	v_mfma_f32_16x16x32_bf16 v[68:71], v[154:157], v[172:175], v[68:71]
	v_mfma_f32_16x16x32_bf16 v[64:67], v[164:167], v[172:175], v[64:67]
	v_mfma_f32_16x16x32_bf16 v[52:55], v[154:157], v[180:183], v[52:55]
	v_mfma_f32_16x16x32_bf16 v[48:51], v[164:167], v[180:183], v[48:51]
	v_mfma_f32_16x16x32_bf16 v[44:47], v[154:157], v[188:191], v[44:47]
	v_mfma_f32_16x16x32_bf16 v[40:43], v[164:167], v[188:191], v[40:43]
	v_mfma_f32_16x16x32_bf16 v[36:39], v[154:157], v[208:211], v[36:39]
	v_mfma_f32_16x16x32_bf16 v[32:35], v[164:167], v[208:211], v[32:35]
	v_mfma_f32_16x16x32_bf16 v[68:71], v[160:163], v[176:179], v[68:71]
	v_mfma_f32_16x16x32_bf16 v[64:67], v[168:171], v[176:179], v[64:67]
	v_mfma_f32_16x16x32_bf16 v[52:55], v[160:163], v[184:187], v[52:55]
	v_mfma_f32_16x16x32_bf16 v[48:51], v[168:171], v[184:187], v[48:51]
	v_mfma_f32_16x16x32_bf16 v[44:47], v[160:163], v[204:207], v[44:47]
	v_mfma_f32_16x16x32_bf16 v[40:43], v[168:171], v[204:207], v[40:43]
	v_mfma_f32_16x16x32_bf16 v[36:39], v[160:163], v[212:215], v[36:39]
	v_mfma_f32_16x16x32_bf16 v[32:35], v[168:171], v[212:215], v[32:35]
	s_setprio 0
	s_barrier
; #define PG8_STAGE(bufoff, gbase, voff) do { _Pragma("unroll") for (int _i = 0; _i < 2; ++_i) \
;         __builtin_amdgcn_global_load_lds((const unsigned*)((const char*)(gbase) + (voff)[_i]), (LAS unsigned*)(lds + (bufoff) + ldsw + _i * 8192), 16, 0, 0); } while (0)
; #define PG8_LDA(dst, b, h) do { _Pragma("unroll") for (int m = 0; m < 4; ++m) _Pragma("unroll") for (int k = 0; k < 2; ++k) dst[m][k] = *(const LAS bf16x8*)(lds + PG8_SA(b, h) + aoff + m * 2048 + k * 1024); } while (0)
; #define PG8_MMA(ai, bj, At, Bt) do { __builtin_amdgcn_s_setprio(1); _Pragma("unroll") for (int m = 0; m < 4; ++m) _Pragma("unroll") for (int n = 0; n < 2; ++n) _Pragma("unroll") for (int k = 0; k < 2; ++k) \
;         acc[ai][bj][m][n] = __builtin_amdgcn_mfma_f32_16x16x32_bf16(Bt[n][k], At[m][k], acc[ai][bj][m][n], 0, 0, 0); __builtin_amdgcn_s_setprio(0); } while (0)
; #define PG8_WAIT_V(n) asm volatile("s_waitcnt vmcnt(" #n ")" ::: "memory")
; #define PG8_WAIT_L(n) asm volatile("s_waitcnt lgkmcnt(" #n ")" ::: "memory")
; #define PG8_BAR __builtin_amdgcn_s_barrier()
; #define PG8_SCHED __builtin_amdgcn_sched_barrier(0)
; template <class EpiT, class Sched>
; __device__ __forceinline__ void gemm_phase(LAS unsigned char* lds, const Gemm g, const Sched& S, const EpiT& E, int wv) {
;     ...
;             PG8_LDA(At, 1, 1); PG8_STAGE(PG8_SB(1, 0), b3, voffB); PG8_STAGE(PG8_SB(1, 1), b3 + hstepB, voffB); PG8_STAGE(PG8_SA(1, 0), a3, voffA);
;             PG8_WAIT_V(8); PG8_WAIT_L(0); PG8_BAR; PG8_MMA(1, 0, At, B0); PG8_MMA(1, 1, At, B1); PG8_BAR; PG8_SCHED;
;         }
	s_add_i32 s26, s56, s33
	s_mov_b32 m0, s26
	ds_read_b128 v[172:175], v159 offset:49152
	ds_read_b128 v[176:179], v159 offset:50176
	ds_read_b128 v[180:183], v159 offset:51200
	ds_read_b128 v[184:187], v159 offset:52224
	ds_read_b128 v[188:191], v159 offset:53248
	ds_read_b128 v[204:207], v159 offset:54272
	ds_read_b128 v[208:211], v159 offset:55296
	ds_read_b128 v[212:215], v159 offset:56320
	global_load_lds_dwordx4 v192, s[62:63]
	s_add_i32 m0, s26, 0x2000
	s_add_u32 s24, s24, 0x40080
	s_addc_u32 s25, s25, 0
	s_add_i32 s26, s57, s33
	global_load_lds_dwordx4 v140, s[62:63]
	s_mov_b32 m0, s26
	s_nop 0
	global_load_lds_dwordx4 v192, s[24:25]
	s_add_i32 m0, s26, 0x2000
	s_nop 0
	global_load_lds_dwordx4 v140, s[24:25]
	s_mov_b32 m0, s40
	s_nop 0
	global_load_lds_dwordx4 v136, s[64:65]
	s_mov_b32 m0, s41
	s_nop 0
	global_load_lds_dwordx4 v138, s[64:65]
	s_waitcnt vmcnt(8)
	s_waitcnt lgkmcnt(0)
	s_barrier
	s_setprio 1
	s_waitcnt lgkmcnt(0)
	v_mfma_f32_16x16x32_bf16 v[92:95], v[128:131], v[172:175], v[92:95]
	v_mfma_f32_16x16x32_bf16 v[88:91], v[146:149], v[172:175], v[88:91]
	v_mfma_f32_16x16x32_bf16 v[84:87], v[128:131], v[180:183], v[84:87]
	v_mfma_f32_16x16x32_bf16 v[80:83], v[146:149], v[180:183], v[80:83]
	v_mfma_f32_16x16x32_bf16 v[76:79], v[128:131], v[188:191], v[76:79]
	v_mfma_f32_16x16x32_bf16 v[72:75], v[146:149], v[188:191], v[72:75]
	v_mfma_f32_16x16x32_bf16 v[60:63], v[128:131], v[208:211], v[60:63]
	v_mfma_f32_16x16x32_bf16 v[56:59], v[146:149], v[208:211], v[56:59]
	v_mfma_f32_16x16x32_bf16 v[92:95], v[132:135], v[176:179], v[92:95]
	v_mfma_f32_16x16x32_bf16 v[88:91], v[150:153], v[176:179], v[88:91]
	v_mfma_f32_16x16x32_bf16 v[84:87], v[132:135], v[184:187], v[84:87]
	v_mfma_f32_16x16x32_bf16 v[80:83], v[150:153], v[184:187], v[80:83]
	v_mfma_f32_16x16x32_bf16 v[76:79], v[132:135], v[204:207], v[76:79]
	v_mfma_f32_16x16x32_bf16 v[72:75], v[150:153], v[204:207], v[72:75]
	v_mfma_f32_16x16x32_bf16 v[60:63], v[132:135], v[212:215], v[60:63]
	v_mfma_f32_16x16x32_bf16 v[56:59], v[150:153], v[212:215], v[56:59]
	s_setprio 0
	s_setprio 1
	v_mfma_f32_16x16x32_bf16 v[28:31], v[154:157], v[172:175], v[28:31]
	v_mfma_f32_16x16x32_bf16 v[24:27], v[164:167], v[172:175], v[24:27]
	v_mfma_f32_16x16x32_bf16 v[20:23], v[154:157], v[180:183], v[20:23]
	v_mfma_f32_16x16x32_bf16 v[16:19], v[164:167], v[180:183], v[16:19]
	v_mfma_f32_16x16x32_bf16 v[12:15], v[154:157], v[188:191], v[12:15]
	v_mfma_f32_16x16x32_bf16 v[8:11], v[164:167], v[188:191], v[8:11]
	v_mfma_f32_16x16x32_bf16 v[4:7], v[154:157], v[208:211], v[4:7]
	v_mfma_f32_16x16x32_bf16 v[0:3], v[164:167], v[208:211], v[0:3]
	v_mfma_f32_16x16x32_bf16 v[28:31], v[160:163], v[176:179], v[28:31]
	v_mfma_f32_16x16x32_bf16 v[24:27], v[168:171], v[176:179], v[24:27]
	v_mfma_f32_16x16x32_bf16 v[20:23], v[160:163], v[184:187], v[20:23]
	v_mfma_f32_16x16x32_bf16 v[16:19], v[168:171], v[184:187], v[16:19]
	v_mfma_f32_16x16x32_bf16 v[12:15], v[160:163], v[204:207], v[12:15]
	v_mfma_f32_16x16x32_bf16 v[8:11], v[168:171], v[204:207], v[8:11]
	v_mfma_f32_16x16x32_bf16 v[4:7], v[160:163], v[212:215], v[4:7]
	v_mfma_f32_16x16x32_bf16 v[0:3], v[168:171], v[212:215], v[0:3]
	s_setprio 0
	s_barrier
	s_add_i32 s55, s55, 2
	s_add_u32 s22, s22, 0x100
	s_addc_u32 s23, s23, 0
	s_add_u32 s53, s53, 0x100
	s_addc_u32 s54, s54, 0
	s_cmp_gt_u32 s55, 13
	s_cbranch_scc0 .LBB0_1271
	s_and_b64 vcc, exec, s[8:9]
	s_cbranch_vccz .LBB0_1274
	s_barrier

; #define PG8_STAGE(bufoff, gbase, voff) do { _Pragma("unroll") for (int _i = 0; _i < 2; ++_i) \
;         __builtin_amdgcn_global_load_lds((const unsigned*)((const char*)(gbase) + (voff)[_i]), (LAS unsigned*)(lds + (bufoff) + ldsw + _i * 8192), 16, 0, 0); } while (0)
; #define PG8_LDA(dst, b, h) do { _Pragma("unroll") for (int m = 0; m < 4; ++m) _Pragma("unroll") for (int k = 0; k < 2; ++k) dst[m][k] = *(const LAS bf16x8*)(lds + PG8_SA(b, h) + aoff + m * 2048 + k * 1024); } while (0)
; #define PG8_LDB(dst, b, h) do { _Pragma("unroll") for (int n = 0; n < 2; ++n) _Pragma("unroll") for (int k = 0; k < 2; ++k) dst[n][k] = *(const LAS bf16x8*)(lds + PG8_SB(b, h) + boff + n * 2048 + k * 1024); } while (0)
; #define PG8_MMA(ai, bj, At, Bt) do { __builtin_amdgcn_s_setprio(1); _Pragma("unroll") for (int m = 0; m < 4; ++m) _Pragma("unroll") for (int n = 0; n < 2; ++n) _Pragma("unroll") for (int k = 0; k < 2; ++k) \
;         acc[ai][bj][m][n] = __builtin_amdgcn_mfma_f32_16x16x32_bf16(Bt[n][k], At[m][k], acc[ai][bj][m][n], 0, 0, 0); __builtin_amdgcn_s_setprio(0); } while (0)
; #define PG8_WAIT_V(n) asm volatile("s_waitcnt vmcnt(" #n ")" ::: "memory")
; #define PG8_WAIT_L(n) asm volatile("s_waitcnt lgkmcnt(" #n ")" ::: "memory")
; #define PG8_BAR __builtin_amdgcn_s_barrier()
; #define PG8_SCHED __builtin_amdgcn_sched_barrier(0)
; template <class EpiT, class Sched>
; __device__ __forceinline__ void gemm_phase(LAS unsigned char* lds, const Gemm g, const Sched& S, const EpiT& E, int wv) {
;     ...
;         for (int t = 0; t < nt; t += 2) {
;             const bool last = (t == nt - 2);
;             const char* a1 = cA + (size_t)(t + 1) * kstep;
;             const char* a2 = last ? nA : cA + (size_t)(t + 2) * kstep; const char* b2 = last ? nB : cB + (size_t)(t + 2) * kstep;
;             const char* a3 = a2 + kstep; const char* b3 = b2 + kstep;
;             PG8_LDB(B0, 0, 0); PG8_LDB(B1, 0, 1); PG8_SCHED; PG8_LDA(At, 0, 0); PG8_STAGE(PG8_SA(1, 1), a1 + hstepA, voffA);
;             PG8_WAIT_V(8); PG8_WAIT_L(0); PG8_BAR; PG8_MMA(0, 0, At, B0); PG8_MMA(0, 1, At, B1); PG8_BAR; PG8_SCHED;
;             PG8_LDA(At, 0, 1); PG8_STAGE(PG8_SB(0, 0), b2, voffB); PG8_STAGE(PG8_SB(0, 1), b2 + hstepB, voffB); PG8_STAGE(PG8_SA(0, 0), a2, voffA);
;             PG8_WAIT_V(8); PG8_WAIT_L(0); PG8_BAR; PG8_MMA(1, 0, At, B0); PG8_MMA(1, 1, At, B1); PG8_BAR; PG8_SCHED;
.LBB0_1335:
	s_add_u32 s24, s4, 0xfff00080
	s_addc_u32 s25, s5, -1
	s_add_i32 s62, 0, 0x10000
	s_cmp_eq_u32 s59, 60
	s_cselect_b32 s27, s17, s25
	s_cselect_b32 s26, s19, s24
	s_cselect_b32 s25, s11, s58
	s_cselect_b32 s24, s23, s33
	s_add_i32 s64, 0, 0x14000
	v_add_u32_e32 v140, s62, v214
	v_add_u32_e32 v156, s64, v214
	ds_read_b128 v[128:131], v140
	ds_read_b128 v[132:135], v140 offset:1024
	ds_read_b128 v[136:139], v140 offset:2048
	ds_read_b128 v[140:143], v140 offset:3072
	ds_read_b128 v[144:147], v156
	ds_read_b128 v[148:151], v156 offset:1024
	ds_read_b128 v[152:155], v156 offset:2048
	ds_read_b128 v[156:159], v156 offset:3072
	s_add_i32 m0, s38, 0xc000
	ds_read_b128 v[160:163], v215
	ds_read_b128 v[164:167], v215 offset:1024
	ds_read_b128 v[178:181], v215 offset:2048
	ds_read_b128 v[182:185], v215 offset:3072
	ds_read_b128 v[186:189], v215 offset:4096
	ds_read_b128 v[204:207], v215 offset:5120
	ds_read_b128 v[208:211], v215 offset:6144
	ds_read_b128 v[216:219], v215 offset:7168
	global_load_lds_dwordx4 v174, s[4:5]
	s_add_i32 m0, s38, 0xe000
	s_nop 0
	global_load_lds_dwordx4 v176, s[4:5]
	s_waitcnt vmcnt(8)
	s_waitcnt lgkmcnt(0)
	s_barrier
	s_setprio 1
	s_waitcnt lgkmcnt(0)
	v_mfma_f32_16x16x32_bf16 v[124:127], v[128:131], v[160:163], v[124:127]
	v_mfma_f32_16x16x32_bf16 v[120:123], v[136:139], v[160:163], v[120:123]
	v_mfma_f32_16x16x32_bf16 v[116:119], v[128:131], v[178:181], v[116:119]
	v_mfma_f32_16x16x32_bf16 v[112:115], v[136:139], v[178:181], v[112:115]
	v_mfma_f32_16x16x32_bf16 v[108:111], v[128:131], v[186:189], v[108:111]
	v_mfma_f32_16x16x32_bf16 v[104:107], v[136:139], v[186:189], v[104:107]
	v_mfma_f32_16x16x32_bf16 v[100:103], v[128:131], v[208:211], v[100:103]
	v_mfma_f32_16x16x32_bf16 v[96:99], v[136:139], v[208:211], v[96:99]
	v_mfma_f32_16x16x32_bf16 v[124:127], v[132:135], v[164:167], v[124:127]
	v_mfma_f32_16x16x32_bf16 v[120:123], v[140:143], v[164:167], v[120:123]
	v_mfma_f32_16x16x32_bf16 v[116:119], v[132:135], v[182:185], v[116:119]
	v_mfma_f32_16x16x32_bf16 v[112:115], v[140:143], v[182:185], v[112:115]
	v_mfma_f32_16x16x32_bf16 v[108:111], v[132:135], v[204:207], v[108:111]
	v_mfma_f32_16x16x32_bf16 v[104:107], v[140:143], v[204:207], v[104:107]
	v_mfma_f32_16x16x32_bf16 v[100:103], v[132:135], v[216:219], v[100:103]
	v_mfma_f32_16x16x32_bf16 v[96:99], v[140:143], v[216:219], v[96:99]
	s_setprio 0
	s_setprio 1
	v_mfma_f32_16x16x32_bf16 v[60:63], v[144:147], v[160:163], v[60:63]
	v_mfma_f32_16x16x32_bf16 v[56:59], v[152:155], v[160:163], v[56:59]
	v_mfma_f32_16x16x32_bf16 v[52:55], v[144:147], v[178:181], v[52:55]
	v_mfma_f32_16x16x32_bf16 v[48:51], v[152:155], v[178:181], v[48:51]
	v_mfma_f32_16x16x32_bf16 v[44:47], v[144:147], v[186:189], v[44:47]
	v_mfma_f32_16x16x32_bf16 v[40:43], v[152:155], v[186:189], v[40:43]
	v_mfma_f32_16x16x32_bf16 v[36:39], v[144:147], v[208:211], v[36:39]
	v_mfma_f32_16x16x32_bf16 v[32:35], v[152:155], v[208:211], v[32:35]
	v_mfma_f32_16x16x32_bf16 v[60:63], v[148:151], v[164:167], v[60:63]
	v_mfma_f32_16x16x32_bf16 v[56:59], v[156:159], v[164:167], v[56:59]
	v_mfma_f32_16x16x32_bf16 v[52:55], v[148:151], v[182:185], v[52:55]
	v_mfma_f32_16x16x32_bf16 v[48:51], v[156:159], v[182:185], v[48:51]
	v_mfma_f32_16x16x32_bf16 v[44:47], v[148:151], v[204:207], v[44:47]
	v_mfma_f32_16x16x32_bf16 v[40:43], v[156:159], v[204:207], v[40:43]
	v_mfma_f32_16x16x32_bf16 v[36:39], v[148:151], v[216:219], v[36:39]
	v_mfma_f32_16x16x32_bf16 v[32:35], v[156:159], v[216:219], v[32:35]
	s_setprio 0
	s_barrier
	s_add_i32 s62, s62, s37
	s_add_u32 s72, s24, s92
	s_addc_u32 s73, s25, s93
	s_mov_b32 m0, s62
	ds_read_b128 v[160:163], v215 offset:16384
	ds_read_b128 v[164:167], v215 offset:17408
	ds_read_b128 v[178:181], v215 offset:18432
	ds_read_b128 v[182:185], v215 offset:19456
	ds_read_b128 v[186:189], v215 offset:20480
	ds_read_b128 v[204:207], v215 offset:21504
	ds_read_b128 v[208:211], v215 offset:22528
	ds_read_b128 v[216:219], v215 offset:23552
	global_load_lds_dwordx4 v192, s[24:25]
	s_add_i32 m0, s62, 0x2000
	s_add_u32 s62, s24, 0x100000
	s_addc_u32 s63, s25, 0
	s_add_i32 s64, s64, s37
	global_load_lds_dwordx4 v172, s[24:25]
	s_mov_b32 m0, s64
	s_nop 0
	global_load_lds_dwordx4 v192, s[62:63]
	s_add_i32 m0, s64, 0x2000
	s_nop 0
	global_load_lds_dwordx4 v172, s[62:63]
	s_add_u32 s98, s26, s92
	s_addc_u32 s99, s27, s93
	s_mov_b32 m0, s38
	s_nop 0
	global_load_lds_dwordx4 v168, s[26:27]
	s_mov_b32 m0, s39
	s_nop 0
	global_load_lds_dwordx4 v170, s[26:27]
	s_waitcnt vmcnt(8)
	s_waitcnt lgkmcnt(0)
	s_barrier
; #define PG8_STAGE(bufoff, gbase, voff) do { _Pragma("unroll") for (int _i = 0; _i < 2; ++_i) \
;         __builtin_amdgcn_global_load_lds((const unsigned*)((const char*)(gbase) + (voff)[_i]), (LAS unsigned*)(lds + (bufoff) + ldsw + _i * 8192), 16, 0, 0); } while (0)
; #define PG8_LDA(dst, b, h) do { _Pragma("unroll") for (int m = 0; m < 4; ++m) _Pragma("unroll") for (int k = 0; k < 2; ++k) dst[m][k] = *(const LAS bf16x8*)(lds + PG8_SA(b, h) + aoff + m * 2048 + k * 1024); } while (0)
; #define PG8_LDB(dst, b, h) do { _Pragma("unroll") for (int n = 0; n < 2; ++n) _Pragma("unroll") for (int k = 0; k < 2; ++k) dst[n][k] = *(const LAS bf16x8*)(lds + PG8_SB(b, h) + boff + n * 2048 + k * 1024); } while (0)
; #define PG8_MMA(ai, bj, At, Bt) do { __builtin_amdgcn_s_setprio(1); _Pragma("unroll") for (int m = 0; m < 4; ++m) _Pragma("unroll") for (int n = 0; n < 2; ++n) _Pragma("unroll") for (int k = 0; k < 2; ++k) \
;         acc[ai][bj][m][n] = __builtin_amdgcn_mfma_f32_16x16x32_bf16(Bt[n][k], At[m][k], acc[ai][bj][m][n], 0, 0, 0); __builtin_amdgcn_s_setprio(0); } while (0)
; #define PG8_WAIT_V(n) asm volatile("s_waitcnt vmcnt(" #n ")" ::: "memory")
; #define PG8_WAIT_L(n) asm volatile("s_waitcnt lgkmcnt(" #n ")" ::: "memory")
; #define PG8_BAR __builtin_amdgcn_s_barrier()
; #define PG8_SCHED __builtin_amdgcn_sched_barrier(0)
; template <class EpiT, class Sched>
; __device__ __forceinline__ void gemm_phase(LAS unsigned char* lds, const Gemm g, const Sched& S, const EpiT& E, int wv) {
;     ...
;             PG8_WAIT_V(8); PG8_WAIT_L(0); PG8_BAR; PG8_MMA(1, 0, At, B0); PG8_MMA(1, 1, At, B1); PG8_BAR; PG8_SCHED;
;             PG8_LDB(B0, 1, 0); PG8_LDB(B1, 1, 1); PG8_SCHED; PG8_LDA(At, 1, 0); PG8_STAGE(PG8_SA(0, 1), a2 + hstepA, voffA);
;             PG8_WAIT_V(8); PG8_WAIT_L(0); PG8_BAR; PG8_MMA(0, 0, At, B0); PG8_MMA(0, 1, At, B1); PG8_BAR; PG8_SCHED;
;             PG8_LDA(At, 1, 1); PG8_STAGE(PG8_SB(1, 0), b3, voffB); PG8_STAGE(PG8_SB(1, 1), b3 + hstepB, voffB); PG8_STAGE(PG8_SA(1, 0), a3, voffA);
	s_setprio 1
	s_waitcnt lgkmcnt(0)
	v_mfma_f32_16x16x32_bf16 v[92:95], v[128:131], v[160:163], v[92:95]
	v_mfma_f32_16x16x32_bf16 v[88:91], v[136:139], v[160:163], v[88:91]
	v_mfma_f32_16x16x32_bf16 v[84:87], v[128:131], v[178:181], v[84:87]
	v_mfma_f32_16x16x32_bf16 v[80:83], v[136:139], v[178:181], v[80:83]
	v_mfma_f32_16x16x32_bf16 v[76:79], v[128:131], v[186:189], v[76:79]
	v_mfma_f32_16x16x32_bf16 v[72:75], v[136:139], v[186:189], v[72:75]
	v_mfma_f32_16x16x32_bf16 v[68:71], v[128:131], v[208:211], v[68:71]
	v_mfma_f32_16x16x32_bf16 v[64:67], v[136:139], v[208:211], v[64:67]
	v_mfma_f32_16x16x32_bf16 v[92:95], v[132:135], v[164:167], v[92:95]
	v_mfma_f32_16x16x32_bf16 v[88:91], v[140:143], v[164:167], v[88:91]
	v_mfma_f32_16x16x32_bf16 v[84:87], v[132:135], v[182:185], v[84:87]
	v_mfma_f32_16x16x32_bf16 v[80:83], v[140:143], v[182:185], v[80:83]
	v_mfma_f32_16x16x32_bf16 v[76:79], v[132:135], v[204:207], v[76:79]
	v_mfma_f32_16x16x32_bf16 v[72:75], v[140:143], v[204:207], v[72:75]
	v_mfma_f32_16x16x32_bf16 v[68:71], v[132:135], v[216:219], v[68:71]
	v_mfma_f32_16x16x32_bf16 v[64:67], v[140:143], v[216:219], v[64:67]
	s_setprio 0
	s_setprio 1
	v_mfma_f32_16x16x32_bf16 v[28:31], v[144:147], v[160:163], v[28:31]
	v_mfma_f32_16x16x32_bf16 v[24:27], v[152:155], v[160:163], v[24:27]
	v_mfma_f32_16x16x32_bf16 v[20:23], v[144:147], v[178:181], v[20:23]
	v_mfma_f32_16x16x32_bf16 v[16:19], v[152:155], v[178:181], v[16:19]
	v_mfma_f32_16x16x32_bf16 v[12:15], v[144:147], v[186:189], v[12:15]
	v_mfma_f32_16x16x32_bf16 v[8:11], v[152:155], v[186:189], v[8:11]
	v_mfma_f32_16x16x32_bf16 v[4:7], v[144:147], v[208:211], v[4:7]
	v_mfma_f32_16x16x32_bf16 v[0:3], v[152:155], v[208:211], v[0:3]
	v_mfma_f32_16x16x32_bf16 v[28:31], v[148:151], v[164:167], v[28:31]
	v_mfma_f32_16x16x32_bf16 v[24:27], v[156:159], v[164:167], v[24:27]
	v_mfma_f32_16x16x32_bf16 v[20:23], v[148:151], v[182:185], v[20:23]
	v_mfma_f32_16x16x32_bf16 v[16:19], v[156:159], v[182:185], v[16:19]
	v_mfma_f32_16x16x32_bf16 v[12:15], v[148:151], v[204:207], v[12:15]
	v_mfma_f32_16x16x32_bf16 v[8:11], v[156:159], v[204:207], v[8:11]
	v_mfma_f32_16x16x32_bf16 v[4:7], v[148:151], v[216:219], v[4:7]
	v_mfma_f32_16x16x32_bf16 v[0:3], v[156:159], v[216:219], v[0:3]
	s_setprio 0
	s_barrier
	s_add_i32 s62, 0, 0x18000
	s_add_i32 s63, 0, 0x1c000
	v_add_u32_e32 v140, s62, v214
	v_add_u32_e32 v156, s63, v214
	ds_read_b128 v[128:131], v140
	ds_read_b128 v[132:135], v140 offset:1024
	ds_read_b128 v[136:139], v140 offset:2048
	ds_read_b128 v[140:143], v140 offset:3072
	ds_read_b128 v[144:147], v156
	ds_read_b128 v[148:151], v156 offset:1024
	ds_read_b128 v[152:155], v156 offset:2048
	ds_read_b128 v[156:159], v156 offset:3072
	s_add_u32 s26, s26, 0x100000
	s_addc_u32 s27, s27, 0
	s_mov_b32 m0, s40
	ds_read_b128 v[160:163], v215 offset:32768
	ds_read_b128 v[164:167], v215 offset:33792
	ds_read_b128 v[178:181], v215 offset:34816
	ds_read_b128 v[182:185], v215 offset:35840
	ds_read_b128 v[186:189], v215 offset:36864
	ds_read_b128 v[204:207], v215 offset:37888
	ds_read_b128 v[208:211], v215 offset:38912
	ds_read_b128 v[216:219], v215 offset:39936
	global_load_lds_dwordx4 v168, s[26:27]
	s_mov_b32 m0, s41
	s_nop 0
	global_load_lds_dwordx4 v170, s[26:27]
	s_waitcnt vmcnt(8)
	s_waitcnt lgkmcnt(0)
	s_barrier
	s_setprio 1
	s_waitcnt lgkmcnt(0)
	v_mfma_f32_16x16x32_bf16 v[124:127], v[128:131], v[160:163], v[124:127]
	v_mfma_f32_16x16x32_bf16 v[120:123], v[136:139], v[160:163], v[120:123]
	v_mfma_f32_16x16x32_bf16 v[116:119], v[128:131], v[178:181], v[116:119]
	v_mfma_f32_16x16x32_bf16 v[112:115], v[136:139], v[178:181], v[112:115]
	v_mfma_f32_16x16x32_bf16 v[108:111], v[128:131], v[186:189], v[108:111]
	v_mfma_f32_16x16x32_bf16 v[104:107], v[136:139], v[186:189], v[104:107]
	v_mfma_f32_16x16x32_bf16 v[100:103], v[128:131], v[208:211], v[100:103]
	v_mfma_f32_16x16x32_bf16 v[96:99], v[136:139], v[208:211], v[96:99]
	v_mfma_f32_16x16x32_bf16 v[124:127], v[132:135], v[164:167], v[124:127]
	v_mfma_f32_16x16x32_bf16 v[120:123], v[140:143], v[164:167], v[120:123]
	v_mfma_f32_16x16x32_bf16 v[116:119], v[132:135], v[182:185], v[116:119]
	v_mfma_f32_16x16x32_bf16 v[112:115], v[140:143], v[182:185], v[112:115]
	v_mfma_f32_16x16x32_bf16 v[108:111], v[132:135], v[204:207], v[108:111]
	v_mfma_f32_16x16x32_bf16 v[104:107], v[140:143], v[204:207], v[104:107]
	v_mfma_f32_16x16x32_bf16 v[100:103], v[132:135], v[216:219], v[100:103]
	v_mfma_f32_16x16x32_bf16 v[96:99], v[140:143], v[216:219], v[96:99]
	s_setprio 0
	s_setprio 1
	v_mfma_f32_16x16x32_bf16 v[60:63], v[144:147], v[160:163], v[60:63]
	v_mfma_f32_16x16x32_bf16 v[56:59], v[152:155], v[160:163], v[56:59]
	v_mfma_f32_16x16x32_bf16 v[52:55], v[144:147], v[178:181], v[52:55]
	v_mfma_f32_16x16x32_bf16 v[48:51], v[152:155], v[178:181], v[48:51]
	v_mfma_f32_16x16x32_bf16 v[44:47], v[144:147], v[186:189], v[44:47]
	v_mfma_f32_16x16x32_bf16 v[40:43], v[152:155], v[186:189], v[40:43]
	v_mfma_f32_16x16x32_bf16 v[36:39], v[144:147], v[208:211], v[36:39]
	v_mfma_f32_16x16x32_bf16 v[32:35], v[152:155], v[208:211], v[32:35]
	v_mfma_f32_16x16x32_bf16 v[60:63], v[148:151], v[164:167], v[60:63]
	v_mfma_f32_16x16x32_bf16 v[56:59], v[156:159], v[164:167], v[56:59]
	v_mfma_f32_16x16x32_bf16 v[52:55], v[148:151], v[182:185], v[52:55]
	v_mfma_f32_16x16x32_bf16 v[48:51], v[156:159], v[182:185], v[48:51]
	v_mfma_f32_16x16x32_bf16 v[44:47], v[148:151], v[204:207], v[44:47]
	v_mfma_f32_16x16x32_bf16 v[40:43], v[156:159], v[204:207], v[40:43]
	v_mfma_f32_16x16x32_bf16 v[36:39], v[148:151], v[216:219], v[36:39]
	v_mfma_f32_16x16x32_bf16 v[32:35], v[156:159], v[216:219], v[32:35]
	s_setprio 0
	s_barrier
; #define PG8_STAGE(bufoff, gbase, voff) do { _Pragma("unroll") for (int _i = 0; _i < 2; ++_i) \
;         __builtin_amdgcn_global_load_lds((const unsigned*)((const char*)(gbase) + (voff)[_i]), (LAS unsigned*)(lds + (bufoff) + ldsw + _i * 8192), 16, 0, 0); } while (0)
; #define PG8_LDA(dst, b, h) do { _Pragma("unroll") for (int m = 0; m < 4; ++m) _Pragma("unroll") for (int k = 0; k < 2; ++k) dst[m][k] = *(const LAS bf16x8*)(lds + PG8_SA(b, h) + aoff + m * 2048 + k * 1024); } while (0)
; #define PG8_MMA(ai, bj, At, Bt) do { __builtin_amdgcn_s_setprio(1); _Pragma("unroll") for (int m = 0; m < 4; ++m) _Pragma("unroll") for (int n = 0; n < 2; ++n) _Pragma("unroll") for (int k = 0; k < 2; ++k) \
;         acc[ai][bj][m][n] = __builtin_amdgcn_mfma_f32_16x16x32_bf16(Bt[n][k], At[m][k], acc[ai][bj][m][n], 0, 0, 0); __builtin_amdgcn_s_setprio(0); } while (0)
; #define PG8_WAIT_V(n) asm volatile("s_waitcnt vmcnt(" #n ")" ::: "memory")
; #define PG8_WAIT_L(n) asm volatile("s_waitcnt lgkmcnt(" #n ")" ::: "memory")
; #define PG8_BAR __builtin_amdgcn_s_barrier()
; #define PG8_SCHED __builtin_amdgcn_sched_barrier(0)
; template <class EpiT, class Sched>
; __device__ __forceinline__ void gemm_phase(LAS unsigned char* lds, const Gemm g, const Sched& S, const EpiT& E, int wv) {
;     ...
;             PG8_LDA(At, 1, 1); PG8_STAGE(PG8_SB(1, 0), b3, voffB); PG8_STAGE(PG8_SB(1, 1), b3 + hstepB, voffB); PG8_STAGE(PG8_SA(1, 0), a3, voffA);
;             PG8_WAIT_V(8); PG8_WAIT_L(0); PG8_BAR; PG8_MMA(1, 0, At, B0); PG8_MMA(1, 1, At, B1); PG8_BAR; PG8_SCHED;
;         }
	s_add_i32 s26, s62, s37
	s_mov_b32 m0, s26
	ds_read_b128 v[160:163], v215 offset:49152
	ds_read_b128 v[164:167], v215 offset:50176
	ds_read_b128 v[178:181], v215 offset:51200
	ds_read_b128 v[182:185], v215 offset:52224
	ds_read_b128 v[186:189], v215 offset:53248
	ds_read_b128 v[204:207], v215 offset:54272
	ds_read_b128 v[208:211], v215 offset:55296
	ds_read_b128 v[216:219], v215 offset:56320
	global_load_lds_dwordx4 v192, s[72:73]
	s_add_i32 m0, s26, 0x2000
	s_add_u32 s24, s24, 0x100080
	s_addc_u32 s25, s25, 0
	s_add_i32 s26, s63, s37
	global_load_lds_dwordx4 v172, s[72:73]
	s_mov_b32 m0, s26
	s_nop 0
	global_load_lds_dwordx4 v192, s[24:25]
	s_add_i32 m0, s26, 0x2000
	s_nop 0
	global_load_lds_dwordx4 v172, s[24:25]
	s_mov_b32 m0, s50
	s_nop 0
	global_load_lds_dwordx4 v168, s[98:99]
	s_mov_b32 m0, s51
	s_nop 0
	global_load_lds_dwordx4 v170, s[98:99]
	s_waitcnt vmcnt(8)
	s_waitcnt lgkmcnt(0)
	s_barrier
	s_setprio 1
	s_waitcnt lgkmcnt(0)
	v_mfma_f32_16x16x32_bf16 v[92:95], v[128:131], v[160:163], v[92:95]
	v_mfma_f32_16x16x32_bf16 v[88:91], v[136:139], v[160:163], v[88:91]
	v_mfma_f32_16x16x32_bf16 v[84:87], v[128:131], v[178:181], v[84:87]
	v_mfma_f32_16x16x32_bf16 v[80:83], v[136:139], v[178:181], v[80:83]
	v_mfma_f32_16x16x32_bf16 v[76:79], v[128:131], v[186:189], v[76:79]
	v_mfma_f32_16x16x32_bf16 v[72:75], v[136:139], v[186:189], v[72:75]
	v_mfma_f32_16x16x32_bf16 v[68:71], v[128:131], v[208:211], v[68:71]
	v_mfma_f32_16x16x32_bf16 v[64:67], v[136:139], v[208:211], v[64:67]
	v_mfma_f32_16x16x32_bf16 v[92:95], v[132:135], v[164:167], v[92:95]
	v_mfma_f32_16x16x32_bf16 v[88:91], v[140:143], v[164:167], v[88:91]
	v_mfma_f32_16x16x32_bf16 v[84:87], v[132:135], v[182:185], v[84:87]
	v_mfma_f32_16x16x32_bf16 v[80:83], v[140:143], v[182:185], v[80:83]
	v_mfma_f32_16x16x32_bf16 v[76:79], v[132:135], v[204:207], v[76:79]
	v_mfma_f32_16x16x32_bf16 v[72:75], v[140:143], v[204:207], v[72:75]
	v_mfma_f32_16x16x32_bf16 v[68:71], v[132:135], v[216:219], v[68:71]
	v_mfma_f32_16x16x32_bf16 v[64:67], v[140:143], v[216:219], v[64:67]
	s_setprio 0
	s_setprio 1
	v_mfma_f32_16x16x32_bf16 v[28:31], v[144:147], v[160:163], v[28:31]
	v_mfma_f32_16x16x32_bf16 v[24:27], v[152:155], v[160:163], v[24:27]
	v_mfma_f32_16x16x32_bf16 v[20:23], v[144:147], v[178:181], v[20:23]
	v_mfma_f32_16x16x32_bf16 v[16:19], v[152:155], v[178:181], v[16:19]
	v_mfma_f32_16x16x32_bf16 v[12:15], v[144:147], v[186:189], v[12:15]
	v_mfma_f32_16x16x32_bf16 v[8:11], v[152:155], v[186:189], v[8:11]
	v_mfma_f32_16x16x32_bf16 v[4:7], v[144:147], v[208:211], v[4:7]
	v_mfma_f32_16x16x32_bf16 v[0:3], v[152:155], v[208:211], v[0:3]
	v_mfma_f32_16x16x32_bf16 v[28:31], v[148:151], v[164:167], v[28:31]
	v_mfma_f32_16x16x32_bf16 v[24:27], v[156:159], v[164:167], v[24:27]
	v_mfma_f32_16x16x32_bf16 v[20:23], v[148:151], v[182:185], v[20:23]
	v_mfma_f32_16x16x32_bf16 v[16:19], v[156:159], v[182:185], v[16:19]
	v_mfma_f32_16x16x32_bf16 v[12:15], v[148:151], v[204:207], v[12:15]
	v_mfma_f32_16x16x32_bf16 v[8:11], v[156:159], v[204:207], v[8:11]
	v_mfma_f32_16x16x32_bf16 v[4:7], v[148:151], v[216:219], v[4:7]
	v_mfma_f32_16x16x32_bf16 v[0:3], v[156:159], v[216:219], v[0:3]
	s_setprio 0
	s_barrier
	s_add_i32 s59, s59, 2
	s_add_u32 s4, s4, 0x100
	s_addc_u32 s5, s5, 0
	s_add_u32 s33, s33, 0x100
	s_addc_u32 s58, s58, 0
	s_cmp_gt_u32 s59, 61
	s_cbranch_scc0 .LBB0_1335
	s_and_b64 vcc, exec, s[14:15]
	s_cbranch_vccz .LBB0_1338
	s_barrier
